# glu: rcp sigmoid + bias loads hoisted out of job loop; ln_res(which=1): gamma/beta loop-invariant regs, modulation loads batched; walks: counted vmcnt so store acks leave the step critical path; layer
# speedup vs baseline: 1.0391x; 1.0203x over previous
_Z4mega6Params:
	s_load_dwordx4 s[84:87], s[0:1], 0x168
	s_mov_b32 s98, 16
	s_mov_b32 s99, 0
	s_mov_b64 s[88:89], s[0:1]
	v_writelane_b32 v254, s2, 0
	v_and_b32_e32 v206, 0x3ff, v0
	v_cmp_eq_u32_e64 s[2:3], 0, v206
	s_mov_b64 s[0:1], exec
	s_nop 0
	v_writelane_b32 v254, s2, 1
	s_nop 1
	v_writelane_b32 v254, s3, 2
	s_and_b64 s[2:3], s[0:1], s[2:3]
	s_mov_b64 exec, s[2:3]
	s_cbranch_execz .LBB0_2
	s_add_i32 s2, 0, 0x25800
	v_mov_b32_e32 v1, 0
	v_mov_b32_e32 v2, s2
	s_add_i32 s2, 0, 0x25804
	ds_write_b32 v2, v1
	v_mov_b32_e32 v2, s2
	ds_write_b32 v2, v1

.LBB0_78:
.LBB0_79:
	s_load_dword s72, s[82:83], 0x0
	v_mov_b32_e32 v158, v206
	v_readlane_b32 s0, v254, 0
	s_mov_b64 s[54:55], s[88:89]
	s_waitcnt lgkmcnt(0)
	s_mov_b32 s56, s72
	s_cmp_lg_u32 s86, 0
	v_writelane_b32 v255, s54, 3
	s_nop 1
	v_writelane_b32 v255, s55, 4
	s_cbranch_scc0 .LBB0_87
	s_add_i32 s1, s86, -1
	s_mul_hi_i32 s2, s1, 0x2aaaaaab
	s_lshr_b32 s3, s2, 31
	s_ashr_i32 s2, s2, 1
	s_add_i32 s44, s2, s3
	s_mul_i32 s2, s44, 12
	s_sub_i32 s57, s1, s2
	s_cmp_lt_i32 s57, 6
	s_mov_b64 s[2:3], -1
	s_cbranch_scc1 .LBB0_292
	s_cmp_lt_i32 s57, 9
	s_cbranch_scc1 .LBB0_167
	s_cmp_lt_i32 s57, 10
	s_cbranch_scc1 .LBB0_121
	s_cmp_lt_i32 s57, 11
	s_cbranch_scc1 .LBB0_95
	s_cmp_eq_u32 s57, 11
	s_cbranch_scc0 .LBB0_94
	s_add_i32 s1, s86, 10
	s_lshl_b32 s22, s0, 3
	s_cmp_lt_u32 s1, 23
	s_cselect_b64 s[2:3], -1, 0
	s_waitcnt vmcnt(0)
	v_ashrrev_i32_e32 v2, 6, v158
	s_and_b64 s[8:9], s[2:3], exec
	s_mov_b32 s1, 0x8400
	s_cselect_b32 s1, s1, 0x8000
	v_add_u32_e32 v0, s22, v2
	v_cmp_gt_i32_e32 vcc, s1, v0
	s_and_saveexec_b64 s[8:9], vcc
	s_cbranch_execz .LBB0_93
	v_lshlrev_b32_e32 v0, 2, v158
	v_and_b32_e32 v18, 0xfc, v0
	v_and_b32_e32 v0, 64, v209
	v_add_u32_e32 v0, 64, v0
	v_xor_b32_e32 v3, 32, v209
	v_cmp_lt_i32_e32 vcc, v3, v0
	s_add_i32 s12, s86, -13
	s_load_dwordx2 s[10:11], s[54:55], 0x160
	v_cndmask_b32_e32 v3, v209, v3, vcc
	v_lshlrev_b32_e32 v19, 2, v3
	v_xor_b32_e32 v3, 16, v209
	v_cmp_lt_i32_e32 vcc, v3, v0
	s_cmp_gt_u32 s12, 11
	s_load_dwordx4 s[24:27], s[54:55], 0xf0
	s_load_dwordx2 s[28:29], s[54:55], 0x100
	v_cndmask_b32_e32 v3, v209, v3, vcc
	v_lshlrev_b32_e32 v40, 2, v3
	v_xor_b32_e32 v3, 8, v209
	v_cmp_lt_i32_e32 vcc, v3, v0
	s_cselect_b64 s[12:13], -1, 0
	s_lshl_b32 s18, s44, 10
	v_cndmask_b32_e32 v3, v209, v3, vcc
	s_ashr_i32 s19, s18, 31
	v_lshlrev_b32_e32 v41, 2, v3
	v_xor_b32_e32 v3, 4, v209
	s_lshl_b32 s14, s56, 3
	s_lshl_b64 s[18:19], s[18:19], 2
	v_cmp_lt_i32_e32 vcc, v3, v0
	s_waitcnt lgkmcnt(0)
	s_add_u32 s26, s26, s18
	s_addc_u32 s27, s27, s19
	v_cndmask_b32_e32 v3, v209, v3, vcc
	v_lshlrev_b32_e32 v42, 2, v3
	v_xor_b32_e32 v3, 2, v209
	s_add_u32 s24, s24, s18
	v_cmp_lt_i32_e32 vcc, v3, v0
	s_addc_u32 s25, s25, s19
	s_load_dwordx4 s[40:43], s[54:55], 0x150
	s_load_dwordx2 s[18:19], s[54:55], 0x130
	v_cndmask_b32_e32 v3, v209, v3, vcc
	v_lshlrev_b32_e32 v43, 2, v3
	v_xor_b32_e32 v3, 1, v209
	v_cmp_lt_i32_e32 vcc, v3, v0
	s_ashr_i32 s23, s22, 31
	v_or_b32_e32 v4, 0x100, v18
	v_cndmask_b32_e32 v0, v209, v3, vcc
	v_ashrrev_i32_e32 v3, 31, v2
	v_lshlrev_b32_e32 v44, 2, v0
	v_lshlrev_b32_e32 v0, 2, v18
	v_lshl_add_u64 v[28:29], v[2:3], 0, s[22:23]
	v_or_b32_e32 v6, 0x200, v18
	v_or_b32_e32 v8, 0x300, v18
	v_lshl_add_u64 v[20:21], s[24:25], 0, v[0:1]
	v_lshl_add_u64 v[22:23], s[26:27], 0, v[0:1]
	s_waitcnt lgkmcnt(0)
	v_lshl_add_u64 v[10:11], s[18:19], 0, v[0:1]
	s_mov_b64 s[24:25], 0x5000
	v_lshlrev_b32_e32 v0, 1, v18
	s_ashr_i32 s15, s14, 31
	v_lshlrev_b64 v[2:3], 12, v[28:29]
	v_lshl_add_u64 v[24:25], v[10:11], 0, s[24:25]
	v_lshl_add_u64 v[26:27], s[42:43], 0, v[0:1]
	v_lshl_add_u64 v[30:31], s[28:29], 0, v[2:3]
	s_lshl_b64 s[22:23], s[14:15], 12
	s_mov_b64 s[24:25], 0
	v_lshlrev_b32_e32 v32, 2, v4
	v_lshlrev_b32_e32 v34, 2, v6
	v_lshlrev_b32_e32 v36, 2, v8
	global_load_dwordx4 v[80:83], v[20:21], off
	global_load_dwordx4 v[96:99], v[22:23], off
	global_load_dwordx4 v[84:87], v[20:21], off offset:1024
	global_load_dwordx4 v[100:103], v[22:23], off offset:1024
	global_load_dwordx4 v[88:91], v[20:21], off offset:2048
	global_load_dwordx4 v[104:107], v[22:23], off offset:2048
	global_load_dwordx4 v[92:95], v[20:21], off offset:3072
	global_load_dwordx4 v[108:111], v[22:23], off offset:3072
	s_branch .LBB0_89

.LBB0_89:
	v_cmp_lt_i32_e32 vcc, s70, v28
	v_mov_b64_e32 v[4:5], v[28:29]
	v_mov_b64_e32 v[2:3], v[30:31]
	s_and_saveexec_b64 s[26:27], vcc
	v_add_u32_e32 v0, 0xffff8000, v28
	v_lshlrev_b64 v[2:3], 12, v[0:1]
	v_mov_b32_e32 v0, v28
	v_lshl_add_u64 v[2:3], s[40:41], 0, v[2:3]
	v_mov_b64_e32 v[4:5], v[0:1]
	s_or_b64 exec, exec, s[26:27]
	v_cmp_lt_i32_e32 vcc, s70, v28
	v_mov_b32_e32 v0, s11
	v_mov_b32_e32 v6, s43
	s_and_b64 vcc, s[2:3], vcc
	v_cndmask_b32_e32 v7, v0, v6, vcc
	v_mov_b32_e32 v0, s10
	v_mov_b32_e32 v6, s42
	v_cndmask_b32_e32 v6, v0, v6, vcc
	v_lshlrev_b64 v[38:39], 11, v[4:5]
	v_min_i32_e32 v0, 0x8000, v28
	v_lshl_add_u64 v[4:5], v[6:7], 0, v[38:39]
	v_lshlrev_b32_e32 v6, 1, v18
	v_mov_b32_e32 v7, v1
	v_ashrrev_i32_e32 v0, 13, v0
	s_mul_i32 s26, s44, 5
	v_lshl_add_u64 v[4:5], v[4:5], 0, v[6:7]
	v_add_u32_e32 v33, s26, v0
	global_load_dwordx2 v[16:17], v[4:5], off
	global_load_dwordx2 v[66:67], v[4:5], off offset:512
	global_load_dwordx2 v[68:69], v[4:5], off offset:1024
	global_load_dwordx2 v[70:71], v[4:5], off offset:1536
	v_mad_i64_i32 v[46:47], s[26:27], v33, s4, v[24:25]
	global_load_dwordx4 v[4:7], v[46:47], off
	global_load_dwordx4 v[8:11], v[46:47], off offset:1024
	global_load_dwordx4 v[12:15], v[46:47], off offset:2048
	v_lshlrev_b32_e32 v0, 2, v18
	global_load_dwordx4 v[46:49], v[46:47], off offset:3072
	v_lshl_add_u64 v[72:73], v[2:3], 0, v[0:1]
	global_load_dwordx4 v[50:53], v[72:73], off
	global_load_dwordx4 v[54:57], v[72:73], off offset:1024
	global_load_dwordx4 v[58:61], v[72:73], off offset:2048
	global_load_dwordx4 v[62:65], v[72:73], off offset:3072
	s_mov_b32 s26, 0x3fb504f3
	s_waitcnt vmcnt(11)
	v_lshlrev_b32_e32 v2, 16, v16
	v_and_b32_e32 v3, 0xffff0000, v16
	s_waitcnt vmcnt(10)
	v_lshlrev_b32_e32 v74, 16, v66
	v_and_b32_e32 v75, 0xffff0000, v66
	v_lshlrev_b32_e32 v66, 16, v67
	v_and_b32_e32 v67, 0xffff0000, v67
	s_waitcnt vmcnt(9)
	v_lshlrev_b32_e32 v76, 16, v68
	v_and_b32_e32 v77, 0xffff0000, v68
	v_lshlrev_b32_e32 v68, 16, v69
	v_and_b32_e32 v69, 0xffff0000, v69
	s_waitcnt vmcnt(8)
	v_lshlrev_b32_e32 v78, 16, v70
	v_and_b32_e32 v79, 0xffff0000, v70
	v_lshlrev_b32_e32 v70, 16, v71
	v_and_b32_e32 v71, 0xffff0000, v71
	s_waitcnt vmcnt(7)
	v_pk_mul_f32 v[2:3], v[4:5], v[2:3]
	v_lshlrev_b32_e32 v16, 16, v17
	v_and_b32_e32 v17, 0xffff0000, v17
	s_waitcnt vmcnt(6)
	v_pk_mul_f32 v[4:5], v[10:11], v[66:67]
	s_waitcnt vmcnt(5)
	v_pk_mul_f32 v[10:11], v[14:15], v[68:69]
	s_waitcnt vmcnt(4)
	v_pk_mul_f32 v[14:15], v[48:49], v[70:71]
	s_waitcnt vmcnt(3)
	v_pk_fma_f32 v[48:49], v[50:51], s[26:27], v[2:3] op_sel_hi:[1,0,1]
	v_pk_mul_f32 v[6:7], v[6:7], v[16:17]
	v_add_f32_e32 v2, 0, v48
	v_pk_mul_f32 v[16:17], v[46:47], v[78:79]
	v_pk_fma_f32 v[46:47], v[52:53], s[26:27], v[6:7] op_sel_hi:[1,0,1]
	v_add_f32_e32 v2, v49, v2
	v_pk_mul_f32 v[8:9], v[8:9], v[74:75]
	v_add_f32_e32 v2, v46, v2
	s_waitcnt vmcnt(2)
	v_pk_fma_f32 v[52:53], v[54:55], s[26:27], v[8:9] op_sel_hi:[1,0,1]
	v_add_f32_e32 v2, v47, v2
	v_add_f32_e32 v2, v52, v2
	v_pk_fma_f32 v[50:51], v[56:57], s[26:27], v[4:5] op_sel_hi:[1,0,1]
	v_add_f32_e32 v2, v53, v2
	v_pk_mul_f32 v[12:13], v[12:13], v[76:77]
	v_add_f32_e32 v2, v50, v2
	s_waitcnt vmcnt(1)
	v_pk_fma_f32 v[12:13], v[58:59], s[26:27], v[12:13] op_sel_hi:[1,0,1]
	v_add_f32_e32 v2, v51, v2
	v_add_f32_e32 v2, v12, v2
	v_pk_fma_f32 v[10:11], v[60:61], s[26:27], v[10:11] op_sel_hi:[1,0,1]
	v_add_f32_e32 v2, v13, v2
	v_add_f32_e32 v2, v10, v2
	s_waitcnt vmcnt(0)
	v_pk_fma_f32 v[16:17], v[62:63], s[26:27], v[16:17] op_sel_hi:[1,0,1]
	v_add_f32_e32 v2, v11, v2
	v_add_f32_e32 v2, v16, v2
	v_pk_fma_f32 v[14:15], v[64:65], s[26:27], v[14:15] op_sel_hi:[1,0,1]
	v_add_f32_e32 v2, v17, v2
	v_add_f32_e32 v2, v14, v2
	v_add_f32_e32 v2, v15, v2
	ds_bpermute_b32 v3, v19, v2
	s_waitcnt lgkmcnt(0)
	v_add_f32_e32 v2, v2, v3
	ds_bpermute_b32 v3, v40, v2
	s_waitcnt lgkmcnt(0)
	v_add_f32_e32 v2, v2, v3
	ds_bpermute_b32 v3, v41, v2
	s_waitcnt lgkmcnt(0)
	v_add_f32_e32 v2, v2, v3
	ds_bpermute_b32 v3, v42, v2
	s_waitcnt lgkmcnt(0)
	v_add_f32_e32 v2, v2, v3
	ds_bpermute_b32 v3, v43, v2
	s_waitcnt lgkmcnt(0)
	v_add_f32_e32 v35, v2, v3
	ds_bpermute_b32 v37, v44, v35
	s_waitcnt lgkmcnt(0)
	v_add_f32_e32 v35, v35, v37
	v_mul_f32_e32 v54, 0x3a800000, v35
	v_pk_add_f32 v[48:49], v[48:49], v[54:55] op_sel_hi:[1,0] neg_lo:[0,1] neg_hi:[0,1]
	v_pk_add_f32 v[46:47], v[46:47], v[54:55] op_sel_hi:[1,0] neg_lo:[0,1] neg_hi:[0,1]
	v_pk_add_f32 v[58:59], v[10:11], v[54:55] op_sel_hi:[1,0] neg_lo:[0,1] neg_hi:[0,1]
	v_pk_mul_f32 v[10:11], v[48:49], v[48:49]
	v_pk_add_f32 v[56:57], v[12:13], v[54:55] op_sel_hi:[1,0] neg_lo:[0,1] neg_hi:[0,1]
	v_pk_mul_f32 v[12:13], v[46:47], v[46:47]
	v_add_f32_e32 v10, v10, v11
	v_pk_add_f32 v[52:53], v[52:53], v[54:55] op_sel_hi:[1,0] neg_lo:[0,1] neg_hi:[0,1]
	v_add_f32_e32 v10, v12, v10
	v_pk_add_f32 v[50:51], v[50:51], v[54:55] op_sel_hi:[1,0] neg_lo:[0,1] neg_hi:[0,1]
	v_pk_add_f32 v[60:61], v[16:17], v[54:55] op_sel_hi:[1,0] neg_lo:[0,1] neg_hi:[0,1]
	v_pk_add_f32 v[54:55], v[14:15], v[54:55] op_sel_hi:[1,0] neg_lo:[0,1] neg_hi:[0,1]
	v_pk_mul_f32 v[14:15], v[52:53], v[52:53]
	v_add_f32_e32 v10, v13, v10
	v_add_f32_e32 v10, v14, v10
	v_pk_mul_f32 v[16:17], v[50:51], v[50:51]
	v_add_f32_e32 v10, v15, v10
	v_add_f32_e32 v10, v16, v10
	v_pk_mul_f32 v[62:63], v[56:57], v[56:57]
	v_add_f32_e32 v10, v17, v10
	v_add_f32_e32 v10, v62, v10
	v_pk_mul_f32 v[64:65], v[58:59], v[58:59]
	v_add_f32_e32 v10, v63, v10
	v_add_f32_e32 v10, v64, v10
	v_pk_mul_f32 v[66:67], v[60:61], v[60:61]
	v_add_f32_e32 v10, v65, v10
	v_add_f32_e32 v10, v66, v10
	v_pk_mul_f32 v[68:69], v[54:55], v[54:55]
	v_add_f32_e32 v10, v67, v10
	v_add_f32_e32 v10, v68, v10
	v_add_f32_e32 v10, v69, v10
	ds_bpermute_b32 v11, v19, v10
	s_waitcnt lgkmcnt(0)
	v_add_f32_e32 v10, v10, v11
	ds_bpermute_b32 v11, v40, v10
	s_waitcnt lgkmcnt(0)
	v_add_f32_e32 v10, v10, v11
	ds_bpermute_b32 v11, v41, v10
	s_waitcnt lgkmcnt(0)
	v_add_f32_e32 v10, v10, v11
	ds_bpermute_b32 v11, v42, v10
	s_waitcnt lgkmcnt(0)
	v_add_f32_e32 v10, v10, v11
	ds_bpermute_b32 v11, v43, v10
	s_waitcnt lgkmcnt(0)
	v_add_f32_e32 v10, v10, v11
	ds_bpermute_b32 v11, v44, v10
	s_waitcnt lgkmcnt(0)
	v_add_f32_e32 v10, v10, v11
	v_fmamk_f32 v10, v10, 0x3a800000, v208
	v_mul_f32_e32 v11, 0x4b800000, v10
	v_cmp_gt_f32_e32 vcc, s5, v10
	s_nop 1
	v_cndmask_b32_e32 v10, v10, v11, vcc
	v_rsq_f32_e32 v10, v10
	s_nop 0
	v_mul_f32_e32 v11, 0x45800000, v10
	v_cndmask_b32_e32 v62, v10, v11, vcc
	v_pk_mul_f32 v[10:11], v[48:49], v[62:63] op_sel_hi:[1,0]
	v_pk_mul_f32 v[12:13], v[46:47], v[62:63] op_sel_hi:[1,0]
	v_pk_fma_f32 v[2:3], v[80:81], v[10:11], v[96:97]
	v_pk_fma_f32 v[4:5], v[82:83], v[12:13], v[98:99]
	global_store_dwordx4 v[72:73], v[2:5], off
	v_pk_mul_f32 v[14:15], v[52:53], v[62:63] op_sel_hi:[1,0]
	v_pk_mul_f32 v[16:17], v[50:51], v[62:63] op_sel_hi:[1,0]
	v_pk_mul_f32 v[46:47], v[56:57], v[62:63] op_sel_hi:[1,0]
	v_pk_mul_f32 v[48:49], v[58:59], v[62:63] op_sel_hi:[1,0]
	v_pk_mul_f32 v[50:51], v[60:61], v[62:63] op_sel_hi:[1,0]
	v_pk_mul_f32 v[52:53], v[54:55], v[62:63] op_sel_hi:[1,0]
	s_andn2_b64 vcc, exec, s[12:13]
	v_pk_fma_f32 v[6:7], v[84:85], v[14:15], v[100:101]
	v_pk_fma_f32 v[8:9], v[86:87], v[16:17], v[102:103]
	global_store_dwordx4 v[72:73], v[6:9], off offset:1024
	v_pk_fma_f32 v[10:11], v[88:89], v[46:47], v[104:105]
	v_pk_fma_f32 v[12:13], v[90:91], v[48:49], v[106:107]
	global_store_dwordx4 v[72:73], v[10:13], off offset:2048
	v_pk_fma_f32 v[14:15], v[92:93], v[50:51], v[108:109]
	v_pk_fma_f32 v[16:17], v[94:95], v[52:53], v[110:111]
	global_store_dwordx4 v[72:73], v[14:17], off offset:3072
	s_cbranch_vccnz .LBB0_88
	v_add_f32_e32 v35, 0, v2
	v_add_f32_e32 v35, v3, v35
	v_add_f32_e32 v35, v4, v35
	v_add_f32_e32 v35, v5, v35
	v_add_f32_e32 v35, v6, v35
	v_add_f32_e32 v35, v7, v35
	v_add_f32_e32 v35, v8, v35
	v_add_f32_e32 v35, v9, v35
	v_add_f32_e32 v35, v10, v35
	v_add_f32_e32 v35, v11, v35
	v_add_f32_e32 v35, v12, v35
	v_add_f32_e32 v35, v13, v35
	v_add_f32_e32 v35, v14, v35
	v_add_f32_e32 v35, v15, v35
	v_add_f32_e32 v35, v16, v35
	v_add_f32_e32 v35, v17, v35
	ds_bpermute_b32 v37, v19, v35
	v_add_u32_e32 v33, 5, v33
	v_mov_b64_e32 v[46:47], s[18:19]
	v_mad_i64_i32 v[50:51], s[26:27], v33, s4, v[46:47]
	s_waitcnt lgkmcnt(0)
	v_add_f32_e32 v35, v35, v37
	ds_bpermute_b32 v37, v40, v35
	s_mov_b64 s[26:27], 0x1000
	v_lshl_add_u64 v[54:55], v[50:51], 0, s[26:27]
	v_lshl_add_u64 v[46:47], v[54:55], 0, v[0:1]
	global_load_dwordx4 v[112:115], v[46:47], off
	global_load_dwordx4 v[116:119], v[46:47], off offset:1024
	global_load_dwordx4 v[120:123], v[46:47], off offset:2048
	global_load_dwordx4 v[124:127], v[46:47], off offset:3072
	s_waitcnt lgkmcnt(0)
	v_add_f32_e32 v35, v35, v37
	ds_bpermute_b32 v37, v41, v35
	v_lshl_add_u64 v[56:57], v[50:51], 0, v[0:1]
	global_load_dwordx4 v[128:131], v[56:57], off
	global_load_dwordx4 v[132:135], v[56:57], off offset:1024
	global_load_dwordx4 v[136:139], v[56:57], off offset:2048
	global_load_dwordx4 v[140:143], v[56:57], off offset:3072
	v_lshl_add_u64 v[38:39], v[26:27], 0, v[38:39]
	s_waitcnt lgkmcnt(0)
	v_add_f32_e32 v35, v35, v37
	ds_bpermute_b32 v37, v42, v35
	s_waitcnt lgkmcnt(0)
	v_add_f32_e32 v35, v35, v37
	ds_bpermute_b32 v37, v43, v35
	s_waitcnt lgkmcnt(0)
	v_add_f32_e32 v33, v35, v37
	ds_bpermute_b32 v35, v44, v33
	v_mov_b32_e32 v37, v1
	s_waitcnt lgkmcnt(0)
	v_add_f32_e32 v0, v33, v35
	v_mul_f32_e32 v0, 0x3a800000, v0
	v_pk_add_f32 v[2:3], v[2:3], v[0:1] op_sel_hi:[1,0] neg_lo:[0,1] neg_hi:[0,1]
	v_pk_add_f32 v[4:5], v[4:5], v[0:1] op_sel_hi:[1,0] neg_lo:[0,1] neg_hi:[0,1]
	v_pk_add_f32 v[58:59], v[8:9], v[0:1] op_sel_hi:[1,0] neg_lo:[0,1] neg_hi:[0,1]
	v_pk_mul_f32 v[8:9], v[2:3], v[2:3]
	v_pk_add_f32 v[60:61], v[6:7], v[0:1] op_sel_hi:[1,0] neg_lo:[0,1] neg_hi:[0,1]
	v_pk_add_f32 v[12:13], v[12:13], v[0:1] op_sel_hi:[1,0] neg_lo:[0,1] neg_hi:[0,1]
	v_pk_add_f32 v[10:11], v[10:11], v[0:1] op_sel_hi:[1,0] neg_lo:[0,1] neg_hi:[0,1]
	v_pk_add_f32 v[16:17], v[16:17], v[0:1] op_sel_hi:[1,0] neg_lo:[0,1] neg_hi:[0,1]
	v_pk_add_f32 v[14:15], v[14:15], v[0:1] op_sel_hi:[1,0] neg_lo:[0,1] neg_hi:[0,1]
	v_pk_mul_f32 v[6:7], v[4:5], v[4:5]
	v_add_f32_e32 v0, v8, v9
	v_add_f32_e32 v0, v6, v0
	v_pk_mul_f32 v[64:65], v[60:61], v[60:61]
	v_add_f32_e32 v0, v7, v0
	v_add_f32_e32 v0, v64, v0
	v_pk_mul_f32 v[62:63], v[58:59], v[58:59]
	v_add_f32_e32 v0, v65, v0
	v_add_f32_e32 v0, v62, v0
	v_pk_mul_f32 v[68:69], v[10:11], v[10:11]
	v_add_f32_e32 v0, v63, v0
	v_add_f32_e32 v0, v68, v0
	v_pk_mul_f32 v[66:67], v[12:13], v[12:13]
	v_add_f32_e32 v0, v69, v0
	v_add_f32_e32 v0, v66, v0
	v_pk_mul_f32 v[72:73], v[14:15], v[14:15]
	v_add_f32_e32 v0, v67, v0
	v_add_f32_e32 v0, v72, v0
	v_pk_mul_f32 v[70:71], v[16:17], v[16:17]
	v_add_f32_e32 v0, v73, v0
	v_add_f32_e32 v0, v70, v0
	v_add_f32_e32 v0, v71, v0
	ds_bpermute_b32 v6, v19, v0
	v_mov_b32_e32 v33, v1
	v_mov_b32_e32 v35, v1
	s_waitcnt lgkmcnt(0)
	v_add_f32_e32 v0, v0, v6
	ds_bpermute_b32 v6, v40, v0
	s_waitcnt lgkmcnt(0)
	v_add_f32_e32 v0, v0, v6
	ds_bpermute_b32 v6, v41, v0
	s_waitcnt lgkmcnt(0)
	v_add_f32_e32 v0, v0, v6
	ds_bpermute_b32 v6, v42, v0
	s_waitcnt vmcnt(0)
	v_pk_add_f32 v[8:9], v[114:115], 1.0 op_sel_hi:[1,0]
	s_waitcnt lgkmcnt(0)
	v_add_f32_e32 v0, v0, v6
	ds_bpermute_b32 v6, v43, v0
	v_pk_add_f32 v[46:47], v[112:113], 1.0 op_sel_hi:[1,0]
	s_waitcnt lgkmcnt(0)
	v_add_f32_e32 v0, v0, v6
	ds_bpermute_b32 v6, v44, v0
	s_waitcnt lgkmcnt(0)
	v_add_f32_e32 v0, v0, v6
	v_fmamk_f32 v0, v0, 0x3a800000, v208
	v_mul_f32_e32 v6, 0x4b800000, v0
	v_cmp_gt_f32_e32 vcc, s5, v0
	s_nop 1
	v_cndmask_b32_e32 v0, v0, v6, vcc
	v_rsq_f32_e32 v0, v0
	v_lshl_add_u64 v[6:7], v[54:55], 0, v[32:33]
	v_mul_f32_e32 v33, 0x45800000, v0
	v_cndmask_b32_e32 v0, v0, v33, vcc
	v_pk_mul_f32 v[2:3], v[2:3], v[0:1] op_sel_hi:[1,0]
	v_pk_mul_f32 v[4:5], v[4:5], v[0:1] op_sel_hi:[1,0]
	v_pk_fma_f32 v[2:3], v[46:47], v[2:3], v[128:129]
	v_pk_fma_f32 v[4:5], v[8:9], v[4:5], v[130:131]
	v_cvt_pk_bf16_f32 v2, v2, v3
	v_cvt_pk_bf16_f32 v3, v4, v5
	global_store_dwordx2 v[38:39], v[2:3], off
	v_pk_mul_f32 v[48:49], v[60:61], v[0:1] op_sel_hi:[1,0]
	v_pk_mul_f32 v[50:51], v[58:59], v[0:1] op_sel_hi:[1,0]
	v_lshl_add_u64 v[46:47], v[54:55], 0, v[34:35]
	v_pk_mul_f32 v[10:11], v[10:11], v[0:1] op_sel_hi:[1,0]
	v_pk_mul_f32 v[12:13], v[12:13], v[0:1] op_sel_hi:[1,0]
	v_pk_add_f32 v[2:3], v[116:117], 1.0 op_sel_hi:[1,0]
	v_pk_add_f32 v[4:5], v[118:119], 1.0 op_sel_hi:[1,0]
	v_pk_fma_f32 v[2:3], v[2:3], v[48:49], v[132:133]
	v_pk_fma_f32 v[4:5], v[4:5], v[50:51], v[134:135]
	v_cvt_pk_bf16_f32 v2, v2, v3
	v_cvt_pk_bf16_f32 v3, v4, v5
	global_store_dwordx2 v[38:39], v[2:3], off offset:512
	v_lshl_add_u64 v[46:47], v[54:55], 0, v[36:37]
	v_pk_add_f32 v[2:3], v[120:121], 1.0 op_sel_hi:[1,0]
	v_pk_add_f32 v[4:5], v[122:123], 1.0 op_sel_hi:[1,0]
	v_pk_fma_f32 v[2:3], v[2:3], v[10:11], v[136:137]
	v_pk_fma_f32 v[4:5], v[4:5], v[12:13], v[138:139]
	v_cvt_pk_bf16_f32 v2, v2, v3
	v_cvt_pk_bf16_f32 v3, v4, v5
	global_store_dwordx2 v[38:39], v[2:3], off offset:1024
	v_pk_mul_f32 v[10:11], v[14:15], v[0:1] op_sel_hi:[1,0]
	v_pk_mul_f32 v[12:13], v[16:17], v[0:1] op_sel_hi:[1,0]
	v_pk_add_f32 v[2:3], v[124:125], 1.0 op_sel_hi:[1,0]
	v_pk_add_f32 v[4:5], v[126:127], 1.0 op_sel_hi:[1,0]
	v_pk_fma_f32 v[2:3], v[2:3], v[10:11], v[140:141]
	v_pk_fma_f32 v[4:5], v[4:5], v[12:13], v[142:143]
	v_cvt_pk_bf16_f32 v2, v2, v3
	v_cvt_pk_bf16_f32 v3, v4, v5
	global_store_dwordx2 v[38:39], v[2:3], off offset:1536
	s_branch .LBB0_88

.LBB0_121:
	s_andn2_b64 vcc, exec, s[2:3]
	s_cbranch_vccnz .LBB0_166
	s_add_i32 s1, s86, -13
	s_cmp_lt_u32 s1, 12
	s_mov_b32 s1, 0x5ac00
	s_cselect_b32 s76, 0x58000, s1
	s_ashr_i32 s1, s0, 31
	s_mov_b32 s18, s57
	s_lshl_b64 s[14:15], s[0:1], 9
	s_ashr_i32 s57, s56, 31
	s_add_i32 s2, s86, 10
	s_cmp_lt_u32 s2, 23
	s_cselect_b64 s[8:9], -1, 0
	s_cmp_gt_u32 s2, 22
	s_cbranch_scc1 .LBB0_128
	s_cmp_eq_u32 s56, 0x100
	s_cbranch_scc0 .Lconv_orig0
	s_cmp_gt_i32 s0, 21
	s_cbranch_scc1 .Lconv_lat0
	s_add_u32 s14, s14, 0x58000
	s_addc_u32 s15, s15, 0
	s_mov_b64 s[10:11], 0x4000
	s_mov_b64 s[12:13], s[76:77]
	s_branch .LBB0_129
.Lconv_lat0:
	s_add_i32 s2, s0, -22
	s_lshl_b32 s14, s2, 9
	s_mov_b32 s15, 0
	s_mov_b64 s[10:11], 0x1d400
	s_mov_b64 s[12:13], 0x57c00
	s_branch .LBB0_129
.Lconv_orig0:
	s_cmp_gt_i32 s0, 15
	s_mov_b64 s[12:13], -1
	s_cbranch_scc0 .LBB0_125
	s_add_i32 s2, s0, -16
	s_mov_b32 s3, s77
	s_lshl_b64 s[2:3], s[2:3], 9
	s_lshl_b64 s[10:11], s[56:57], 9
	s_add_u32 s10, s10, 0xffffe000
	s_addc_u32 s11, s11, -1
	s_mov_b64 s[12:13], 0

.LBB0_161:
	s_or_b64 exec, exec, s[14:15]
	s_movk_i32 s27, 0x5ff
	v_readlane_b32 s28, v254, 62
	s_cmp_eq_u32 s86, 10
	s_cbranch_scc0 .LBB0_166
	s_cmp_eq_u32 s56, 0x100
	s_cbranch_scc0 .Lconv_tail_orig
	s_cmp_eq_u32 s99, 1
	s_cbranch_scc1 .Lconv_tail_done2
	s_mov_b32 s98, 22
	s_cmp_lt_i32 s0, 16
	s_cbranch_scc1 .Lconv_ctx_gemm
	s_cmp_lt_i32 s0, 22
	s_cbranch_scc0 .LBB0_166
	s_waitcnt vmcnt(0) lgkmcnt(0)
	s_barrier
	v_cmp_eq_u32_e32 vcc, 0, v158
	s_and_saveexec_b64 s[8:9], vcc
	s_cbranch_execz .Lconv_arr_done
	s_load_dwordx2 s[10:11], s[54:55], 0x168
	buffer_wbl2 sc1
	s_waitcnt lgkmcnt(0)
	s_waitcnt vmcnt(0)
	s_add_u32 s10, s10, 0x3900
	s_addc_u32 s11, s11, 0
	v_mov_b32_e32 v0, 1
	s_nop 4
	global_atomic_add v1, v0, s[10:11]
.Lconv_arr_done:
	s_or_b64 exec, exec, s[8:9]
	s_mov_b32 s99, 1
	s_add_i32 s2, s0, -16
	s_lshl_b32 s14, s2, 9
	s_add_u32 s14, s14, 0x57c00
	s_mov_b32 s15, 0
	s_mov_b64 s[10:11], 0x100000
	s_mov_b64 s[12:13], 0x58000
	s_mov_b32 s18, s57
	s_branch .LBB0_129
.Lconv_tail_done2:
	s_mov_b32 s99, 0
	s_branch .LBB0_166
.Lconv_tail_orig:
	s_mov_b32 s98, 16
	s_cmp_lt_i32 s0, 16
	s_cbranch_scc0 .LBB0_166
.Lconv_ctx_gemm:
	s_waitcnt vmcnt(0)
	v_cmp_eq_u32_e32 vcc, 0, v158
	s_waitcnt vmcnt(0) lgkmcnt(0)
	s_barrier
	s_and_saveexec_b64 s[8:9], vcc
	s_cbranch_execz .LBB0_235
	s_load_dwordx2 s[10:11], s[54:55], 0x168
	s_mov_b64 s[12:13], exec
	buffer_wbl2 sc1
	s_waitcnt lgkmcnt(0)
	s_waitcnt vmcnt(0)
	v_mbcnt_lo_u32_b32 v0, s12, 0
	s_add_u32 s10, s10, 0x3900
	v_mbcnt_hi_u32_b32 v0, s13, v0
	s_addc_u32 s11, s11, 0
	v_cmp_eq_u32_e32 vcc, 0, v0
	s_and_saveexec_b64 s[14:15], vcc
	s_cbranch_execz .LBB0_165
	s_bcnt1_i32_b64 s12, s[12:13]
	v_mov_b32_e32 v0, s12
	global_atomic_add v1, v0, s[10:11]

.LBB0_212:
	global_load_dword v0, v1, s[10:11] sc1
	s_mov_b64 s[12:13], -1
	s_waitcnt vmcnt(0)
	v_cmp_le_u32_e32 vcc, s98, v0
	s_cbranch_vccnz .LBB0_211
	s_cmp_lg_u32 s14, 0
	s_sleep 1
	s_cbranch_scc0 .LBB0_210
	global_load_dword v0, v1, s[10:11] sc1
	s_waitcnt vmcnt(0)
	v_cmp_gt_u32_e32 vcc, s98, v0
	s_cbranch_vccz .LBB0_211
	s_sleep 1
	global_load_dword v0, v1, s[10:11] sc1
	s_waitcnt vmcnt(0)
	v_cmp_gt_u32_e32 vcc, s98, v0
	s_cbranch_vccz .LBB0_211
	s_sleep 1
	global_load_dword v0, v1, s[10:11] sc1
	s_waitcnt vmcnt(0)
	v_cmp_gt_u32_e32 vcc, s98, v0
	s_cbranch_vccz .LBB0_211
	s_sleep 1
	global_load_dword v0, v1, s[10:11] sc1
	s_waitcnt vmcnt(0)
	v_cmp_gt_u32_e32 vcc, s98, v0
	s_cbranch_vccz .LBB0_211
	s_sleep 1
	global_load_dword v0, v1, s[10:11] sc1
	s_waitcnt vmcnt(0)
	v_cmp_gt_u32_e32 vcc, s98, v0
	s_cbranch_vccz .LBB0_211
	s_sleep 1
	global_load_dword v0, v1, s[10:11] sc1
	s_waitcnt vmcnt(0)
	v_cmp_gt_u32_e32 vcc, s98, v0
	s_cbranch_vccz .LBB0_211
	s_sleep 1
	global_load_dword v0, v1, s[10:11] sc1
	s_waitcnt vmcnt(0)
	v_cmp_gt_u32_e32 vcc, s98, v0
	s_cbranch_vccz .LBB0_211
	s_sleep 1
	s_add_i32 s14, s14, -8
	s_mov_b64 s[12:13], 0
	s_branch .LBB0_211

.LBB0_292:
	s_andn2_b64 vcc, exec, s[2:3]
	s_cbranch_vccnz .LBB0_687
	s_cmp_lt_i32 s57, 3
	s_mov_b64 s[2:3], -1
	s_cbranch_scc1 .LBB0_564
	s_cmp_lt_i32 s57, 4
	s_cbranch_scc1 .LBB0_329
	s_cmp_gt_i32 s57, 4
	s_mov_b64 s[28:29], 0xc600000
	s_mov_b64 s[30:31], 0xf780000
	s_cbranch_scc0 .LBB0_300
	s_load_dwordx2 s[2:3], s[54:55], 0x128
	s_ashr_i32 s45, s44, 31
	s_lshl_b64 s[8:9], s[44:45], 17
	s_waitcnt vmcnt(0)
	v_add_u32_e32 v6, 0x200, v158
	v_lshlrev_b32_e32 v0, 4, v158
	s_waitcnt lgkmcnt(0)
	s_add_u32 s2, s2, s8
	v_ashrrev_i32_e32 v68, 5, v158
	v_ashrrev_i32_e32 v70, 5, v6
	s_addc_u32 s3, s3, s9
	v_and_b32_e32 v0, 0x1f0, v0
	v_ashrrev_i32_e32 v69, 31, v68
	v_ashrrev_i32_e32 v71, 31, v70
	v_add_u32_e32 v12, 0x400, v158
	v_add_u32_e32 v14, 0x600, v158
	v_lshl_add_u64 v[2:3], s[2:3], 0, v[0:1]
	v_lshlrev_b64 v[4:5], 9, v[68:69]
	v_lshlrev_b64 v[6:7], 9, v[70:71]
	v_ashrrev_i32_e32 v72, 5, v12
	v_ashrrev_i32_e32 v74, 5, v14
	v_lshl_add_u64 v[4:5], v[2:3], 0, v[4:5]
	v_lshl_add_u64 v[8:9], v[2:3], 0, v[6:7]
	v_ashrrev_i32_e32 v73, 31, v72
	v_ashrrev_i32_e32 v75, 31, v74
	v_add_u32_e32 v20, 0x800, v158
	v_add_u32_e32 v22, 0xa00, v158
	s_waitcnt vmcnt(0)
	s_barrier
	global_load_dwordx4 v[4:7], v[4:5], off
	s_nop 0
	global_load_dwordx4 v[8:11], v[8:9], off
	v_lshlrev_b64 v[12:13], 9, v[72:73]
	v_lshlrev_b64 v[14:15], 9, v[74:75]
	v_ashrrev_i32_e32 v76, 5, v20
	v_ashrrev_i32_e32 v78, 5, v22
	v_lshl_add_u64 v[12:13], v[2:3], 0, v[12:13]
	v_lshl_add_u64 v[16:17], v[2:3], 0, v[14:15]
	v_ashrrev_i32_e32 v77, 31, v76
	v_ashrrev_i32_e32 v79, 31, v78
	v_add_u32_e32 v28, 0xc00, v158
	v_add_u32_e32 v30, 0xe00, v158
	global_load_dwordx4 v[12:15], v[12:13], off
	s_nop 0
	global_load_dwordx4 v[16:19], v[16:17], off
	v_lshlrev_b64 v[20:21], 9, v[76:77]
	v_lshlrev_b64 v[22:23], 9, v[78:79]
	v_ashrrev_i32_e32 v80, 5, v28
	v_ashrrev_i32_e32 v82, 5, v30
	v_lshl_add_u64 v[20:21], v[2:3], 0, v[20:21]
	v_lshl_add_u64 v[24:25], v[2:3], 0, v[22:23]
	v_ashrrev_i32_e32 v81, 31, v80
	v_ashrrev_i32_e32 v83, 31, v82
	v_add_u32_e32 v36, 0x1000, v158
	v_add_u32_e32 v38, 0x1200, v158
	global_load_dwordx4 v[20:23], v[20:21], off
	s_nop 0
	global_load_dwordx4 v[24:27], v[24:25], off
	v_lshlrev_b64 v[28:29], 9, v[80:81]
	v_lshlrev_b64 v[30:31], 9, v[82:83]
	v_ashrrev_i32_e32 v84, 5, v36
	v_ashrrev_i32_e32 v86, 5, v38
	v_lshl_add_u64 v[28:29], v[2:3], 0, v[28:29]
	v_lshl_add_u64 v[32:33], v[2:3], 0, v[30:31]
	v_ashrrev_i32_e32 v85, 31, v84
	v_ashrrev_i32_e32 v87, 31, v86
	v_add_u32_e32 v44, 0x1400, v158
	v_add_u32_e32 v46, 0x1600, v158
	global_load_dwordx4 v[28:31], v[28:29], off
	s_nop 0
	global_load_dwordx4 v[32:35], v[32:33], off
	v_lshlrev_b64 v[36:37], 9, v[84:85]
	v_lshlrev_b64 v[38:39], 9, v[86:87]
	v_ashrrev_i32_e32 v88, 5, v44
	v_ashrrev_i32_e32 v90, 5, v46
	v_lshl_add_u64 v[36:37], v[2:3], 0, v[36:37]
	v_lshl_add_u64 v[40:41], v[2:3], 0, v[38:39]
	v_ashrrev_i32_e32 v89, 31, v88
	v_ashrrev_i32_e32 v91, 31, v90
	v_add_u32_e32 v52, 0x1800, v158
	v_add_u32_e32 v54, 0x1a00, v158
	global_load_dwordx4 v[36:39], v[36:37], off
	s_nop 0
	global_load_dwordx4 v[40:43], v[40:41], off
	v_lshlrev_b64 v[44:45], 9, v[88:89]
	v_lshlrev_b64 v[46:47], 9, v[90:91]
	v_ashrrev_i32_e32 v92, 5, v52
	v_ashrrev_i32_e32 v94, 5, v54
	v_add_u32_e32 v60, 0x1c00, v158
	v_lshl_add_u64 v[44:45], v[2:3], 0, v[44:45]
	v_lshl_add_u64 v[48:49], v[2:3], 0, v[46:47]
	v_ashrrev_i32_e32 v93, 31, v92
	v_ashrrev_i32_e32 v95, 31, v94
	v_ashrrev_i32_e32 v96, 5, v60
	v_add_u32_e32 v64, 0x1e00, v158
	global_load_dwordx4 v[44:47], v[44:45], off
	s_nop 0
	global_load_dwordx4 v[48:51], v[48:49], off
	v_lshlrev_b64 v[52:53], 9, v[92:93]
	v_lshlrev_b64 v[54:55], 9, v[94:95]
	v_ashrrev_i32_e32 v97, 31, v96
	v_ashrrev_i32_e32 v98, 5, v64
	v_lshl_add_u64 v[52:53], v[2:3], 0, v[52:53]
	v_lshl_add_u64 v[56:57], v[2:3], 0, v[54:55]
	v_lshlrev_b64 v[60:61], 9, v[96:97]
	v_ashrrev_i32_e32 v99, 31, v98
	global_load_dwordx4 v[52:55], v[52:53], off
	s_nop 0
	global_load_dwordx4 v[56:59], v[56:57], off
	v_lshl_add_u64 v[60:61], v[2:3], 0, v[60:61]
	v_lshlrev_b64 v[64:65], 9, v[98:99]
	global_load_dwordx4 v[60:63], v[60:61], off
	v_lshl_add_u64 v[2:3], v[2:3], 0, v[64:65]
	global_load_dwordx4 v[64:67], v[2:3], off
	v_add_u32_e32 v0, 0, v0
	v_mad_u64_u32 v[68:69], s[2:3], v68, s6, v[0:1]
	v_ashrrev_i32_e32 v2, 6, v158
	s_movk_i32 s1, 0x840
	s_waitcnt vmcnt(15)
	ds_write_b128 v68, v[4:7]
	v_mad_u64_u32 v[4:5], s[2:3], v70, s6, v[0:1]
	s_waitcnt vmcnt(14)
	ds_write_b128 v4, v[8:11]
	v_mad_u64_u32 v[4:5], s[2:3], v72, s6, v[0:1]
	s_waitcnt vmcnt(13)
	ds_write_b128 v4, v[12:15]
	v_mad_u64_u32 v[4:5], s[2:3], v74, s6, v[0:1]
	s_waitcnt vmcnt(12)
	ds_write_b128 v4, v[16:19]
	v_mad_u64_u32 v[4:5], s[2:3], v76, s6, v[0:1]
	s_waitcnt vmcnt(11)
	ds_write_b128 v4, v[20:23]
	v_mad_u64_u32 v[4:5], s[2:3], v78, s6, v[0:1]
	s_waitcnt vmcnt(10)
	ds_write_b128 v4, v[24:27]
	v_mad_u64_u32 v[4:5], s[2:3], v80, s6, v[0:1]
	s_waitcnt vmcnt(9)
	ds_write_b128 v4, v[28:31]
	v_mad_u64_u32 v[4:5], s[2:3], v82, s6, v[0:1]
	s_waitcnt vmcnt(8)
	ds_write_b128 v4, v[32:35]
	v_mad_u64_u32 v[4:5], s[2:3], v84, s6, v[0:1]
	v_lshl_add_u32 v84, s0, 3, v2
	v_cmp_gt_i32_e32 vcc, s1, v84
	s_waitcnt vmcnt(7)
	ds_write_b128 v4, v[36:39]
	v_mad_u64_u32 v[4:5], s[2:3], v86, s6, v[0:1]
	s_waitcnt vmcnt(6)
	ds_write_b128 v4, v[40:43]
	v_mad_u64_u32 v[4:5], s[2:3], v88, s6, v[0:1]
	s_waitcnt vmcnt(5)
	ds_write_b128 v4, v[44:47]
	v_mad_u64_u32 v[4:5], s[2:3], v90, s6, v[0:1]
	s_waitcnt vmcnt(4)
	ds_write_b128 v4, v[48:51]
	v_mad_u64_u32 v[4:5], s[2:3], v92, s6, v[0:1]
	s_waitcnt vmcnt(3)
	ds_write_b128 v4, v[52:55]
	v_mad_u64_u32 v[4:5], s[2:3], v94, s6, v[0:1]
	s_waitcnt vmcnt(2)
	ds_write_b128 v4, v[56:59]
	v_mad_u64_u32 v[4:5], s[2:3], v96, s6, v[0:1]
	s_waitcnt vmcnt(1)
	ds_write_b128 v4, v[60:63]
	v_mad_u64_u32 v[4:5], s[2:3], v98, s6, v[0:1]
	s_waitcnt vmcnt(0)
	ds_write_b128 v4, v[64:67]
	s_waitcnt lgkmcnt(0)
	s_barrier
	s_and_saveexec_b64 s[8:9], vcc
	s_cbranch_execz .LBB0_299
	s_load_dwordx4 s[24:27], s[54:55], 0x158
	s_load_dwordx2 s[2:3], s[54:55], 0x80
	v_and_b32_e32 v3, 15, v158
	v_bfe_u32 v5, v158, 4, 2
	v_lshlrev_b32_e32 v0, 3, v5
	s_waitcnt lgkmcnt(0)
	s_add_u32 s12, s26, 0x15a80000
	s_addc_u32 s13, s27, 0
	s_lshl_b32 s10, s44, 8
	s_ashr_i32 s11, s10, 31
	s_lshl_b64 s[10:11], s[10:11], 2
	s_add_u32 s2, s2, s10
	v_lshlrev_b32_e32 v4, 2, v5
	v_lshlrev_b32_e32 v6, 4, v5
	v_mul_u32_u24_e32 v5, 0x210, v3
	v_lshlrev_b32_e32 v2, 4, v2
	s_addc_u32 s3, s3, s11
	v_mov_b32_e32 v7, v1
	v_add3_u32 v85, 0, v6, v5
	v_lshl_add_u32 v2, s0, 7, v2
	v_lshl_add_u64 v[42:43], s[2:3], 0, v[6:7]
	v_lshl_add_u64 v[44:45], s[24:25], 0, v[0:1]
	v_add_u32_e32 v86, 0x10800, v85
	v_add_u32_e32 v87, 0x10840, v85
	v_add_u32_e32 v88, 0x10880, v85
	v_add_u32_e32 v89, 0x108c0, v85
	v_add_u32_e32 v90, 0x10900, v85
	v_add_u32_e32 v91, 0x10940, v85
	v_add_u32_e32 v92, 0x10980, v85
	v_add_u32_e32 v93, 0x109c0, v85
	v_add_u32_e32 v94, 0x12900, v85
	v_add_u32_e32 v95, 0x12940, v85
	v_add_u32_e32 v96, 0x12980, v85
	v_add_u32_e32 v97, 0x129c0, v85
	v_add_u32_e32 v98, 0x12a00, v85
	v_add_u32_e32 v99, 0x12a40, v85
	v_add_u32_e32 v100, 0x12a80, v85
	v_add_u32_e32 v101, 0x12ac0, v85
	v_add_u32_e32 v102, 0x14a00, v85
	v_add_u32_e32 v103, 0x14a40, v85
	v_add_u32_e32 v104, 0x14a80, v85
	v_add_u32_e32 v105, 0x14ac0, v85
	v_add_u32_e32 v106, 0x14b00, v85
	v_add_u32_e32 v107, 0x14b40, v85
	v_add_u32_e32 v108, 0x14b80, v85
	v_add_u32_e32 v109, 0x14bc0, v85
	v_add_u32_e32 v110, 0x16b00, v85
	v_add_u32_e32 v111, 0x16b40, v85
	v_add_u32_e32 v112, 0x16b80, v85
	v_add_u32_e32 v113, 0x16bc0, v85
	v_add_u32_e32 v114, 0x16c00, v85
	v_add_u32_e32 v115, 0x16c40, v85
	v_add_u32_e32 v116, 0x16c80, v85
	v_add_u32_e32 v117, 0x16cc0, v85
	v_add_u32_e32 v118, 0x18c00, v85
	v_add_u32_e32 v119, 0x18c40, v85
	v_add_u32_e32 v120, 0x18c80, v85
	v_add_u32_e32 v121, 0x18cc0, v85
	v_add_u32_e32 v122, 0x18d00, v85
	v_add_u32_e32 v123, 0x18d40, v85
	v_add_u32_e32 v124, 0x18d80, v85
	v_add_u32_e32 v125, 0x18dc0, v85
	v_add_u32_e32 v126, 0x1ad00, v85
	v_add_u32_e32 v127, 0x1ad40, v85
	v_add_u32_e32 v128, 0x1ad80, v85
	v_add_u32_e32 v129, 0x1adc0, v85
	v_add_u32_e32 v130, 0x1ae00, v85
	v_add_u32_e32 v131, 0x1ae40, v85
	v_add_u32_e32 v132, 0x1ae80, v85
	v_add_u32_e32 v133, 0x1aec0, v85
	v_add_u32_e32 v134, 0x1ce00, v85
	v_add_u32_e32 v135, 0x1ce40, v85
	v_add_u32_e32 v136, 0x1ce80, v85
	v_add_u32_e32 v137, 0x1cec0, v85
	v_add_u32_e32 v138, 0x1cf00, v85
	v_add_u32_e32 v139, 0x1cf40, v85
	v_add_u32_e32 v140, 0x1cf80, v85
	v_add_u32_e32 v141, 0x1cfc0, v85
	v_add_u32_e32 v142, 0x1ef00, v85
	v_add_u32_e32 v143, 0x1ef40, v85
	v_add_u32_e32 v144, 0x1ef80, v85
	v_add_u32_e32 v145, 0x1efc0, v85
	v_add_u32_e32 v146, 0x1f000, v85
	v_add_u32_e32 v147, 0x1f040, v85
	v_add_u32_e32 v148, 0x1f080, v85
	v_add_u32_e32 v149, 0x1f0c0, v85
	s_lshl_b32 s1, s56, 3
	v_or_b32_e32 v46, v2, v3
	s_lshl_b32 s2, s56, 7
	s_mov_b64 s[22:23], 0
	v_lshlrev_b32_e32 v0, 1, v0
	v_lshlrev_b32_e32 v48, 1, v4
	global_load_dwordx4 v[164:167], v[42:43], off offset:64
	global_load_dwordx4 v[168:171], v[42:43], off offset:128
	global_load_dwordx4 v[172:175], v[42:43], off offset:192
	global_load_dwordx4 v[176:179], v[42:43], off offset:256
	global_load_dwordx4 v[180:183], v[42:43], off offset:320
	global_load_dwordx4 v[184:187], v[42:43], off offset:384
	global_load_dwordx4 v[188:191], v[42:43], off offset:448
	global_load_dwordx4 v[192:195], v[42:43], off offset:512
	global_load_dwordx4 v[196:199], v[42:43], off offset:576
	global_load_dwordx4 v[200:203], v[42:43], off offset:640
	global_load_dwordx4 v[234:237], v[42:43], off offset:704
	global_load_dwordx4 v[238:241], v[42:43], off offset:768
	global_load_dwordx4 v[242:245], v[42:43], off offset:832
	global_load_dwordx4 v[246:249], v[42:43], off offset:896
	global_load_dwordx4 v[250:253], v[42:43], off offset:960
.LBB0_298:
	v_ashrrev_i32_e32 v47, 31, v46
	v_lshlrev_b64 v[2:3], 9, v[46:47]
	v_lshl_add_u64 v[34:35], s[12:13], 0, v[2:3]
	v_lshl_add_u64 v[2:3], v[34:35], 0, v[0:1]
	global_load_dwordx4 v[30:33], v[2:3], off
	global_load_dwordx4 v[26:29], v[2:3], off offset:64
	global_load_dwordx4 v[22:25], v[2:3], off offset:128
	global_load_dwordx4 v[18:21], v[2:3], off offset:192
	global_load_dwordx4 v[14:17], v[2:3], off offset:256
	global_load_dwordx4 v[10:13], v[2:3], off offset:320
	global_load_dwordx4 v[6:9], v[2:3], off offset:384
	s_nop 0
	global_load_dwordx4 v[2:5], v[2:3], off offset:448
	v_mov_b32_e32 v49, v1
	v_lshl_add_u64 v[34:35], v[34:35], 0, v[48:49]
	global_load_dwordx2 v[82:83], v[34:35], off
	global_load_dwordx2 v[80:81], v[34:35], off offset:32
	global_load_dwordx2 v[78:79], v[34:35], off offset:64
	global_load_dwordx2 v[76:77], v[34:35], off offset:96
	global_load_dwordx2 v[74:75], v[34:35], off offset:128
	global_load_dwordx2 v[72:73], v[34:35], off offset:160
	global_load_dwordx2 v[70:71], v[34:35], off offset:192
	global_load_dwordx2 v[68:69], v[34:35], off offset:224
	global_load_dwordx2 v[66:67], v[34:35], off offset:256
	global_load_dwordx2 v[64:65], v[34:35], off offset:288
	global_load_dwordx2 v[62:63], v[34:35], off offset:320
	global_load_dwordx2 v[60:61], v[34:35], off offset:352
	global_load_dwordx2 v[58:59], v[34:35], off offset:384
	global_load_dwordx2 v[56:57], v[34:35], off offset:416
	global_load_dwordx2 v[54:55], v[34:35], off offset:448
	global_load_dwordx2 v[52:53], v[34:35], off offset:480
	v_lshlrev_b64 v[34:35], 11, v[46:47]
	v_lshl_add_u64 v[50:51], v[44:45], 0, v[34:35]
	global_load_dwordx4 v[34:37], v[42:43], off
	ds_read_b128 v[38:41], v85
	ds_read_b128 v[160:163], v85 offset:64
	v_add_u32_e32 v84, s1, v84
	s_movk_i32 s3, 0x83f
	v_add_u32_e32 v46, s2, v46
	s_waitcnt vmcnt(24) lgkmcnt(1)
	v_mfma_f32_16x16x32_bf16 v[38:41], v[38:41], v[30:33], 0
	s_waitcnt vmcnt(23) lgkmcnt(0)
	v_mfma_f32_16x16x32_bf16 v[38:41], v[160:163], v[26:29], v[38:41]
	ds_read_b128 v[160:163], v85 offset:128
	s_waitcnt vmcnt(22) lgkmcnt(0)
	v_mfma_f32_16x16x32_bf16 v[38:41], v[160:163], v[22:25], v[38:41]
	ds_read_b128 v[160:163], v85 offset:192
	s_waitcnt vmcnt(21) lgkmcnt(0)
	v_mfma_f32_16x16x32_bf16 v[38:41], v[160:163], v[18:21], v[38:41]
	ds_read_b128 v[160:163], v85 offset:256
	s_waitcnt vmcnt(20) lgkmcnt(0)
	v_mfma_f32_16x16x32_bf16 v[38:41], v[160:163], v[14:17], v[38:41]
	ds_read_b128 v[160:163], v85 offset:320
	s_waitcnt vmcnt(19) lgkmcnt(0)
	v_mfma_f32_16x16x32_bf16 v[38:41], v[160:163], v[10:13], v[38:41]
	ds_read_b128 v[160:163], v85 offset:384
	s_waitcnt vmcnt(18) lgkmcnt(0)
	v_mfma_f32_16x16x32_bf16 v[38:41], v[160:163], v[6:9], v[38:41]
	ds_read_b128 v[160:163], v85 offset:448
	s_waitcnt vmcnt(17) lgkmcnt(0)
	v_mfma_f32_16x16x32_bf16 v[38:41], v[160:163], v[2:5], v[38:41]
	s_waitcnt vmcnt(0)
	s_nop 6
	v_add_f32_e32 v34, v34, v38
	v_add_f32_e32 v35, v35, v39
	v_mul_f32_e32 v34, 0xbfb8aa3b, v34
	v_mul_f32_e32 v35, 0xbfb8aa3b, v35
	v_exp_f32_e32 v34, v34
	v_exp_f32_e32 v35, v35
	v_lshlrev_b32_e32 v38, 16, v82
	v_and_b32_e32 v39, 0xffff0000, v82
	v_pk_add_f32 v[34:35], v[34:35], 1.0 op_sel_hi:[1,0]
	s_nop 0
	v_rcp_f32_e32 v35, v35
	v_rcp_f32_e32 v34, v34
	s_nop 0
	v_pk_mul_f32 v[34:35], v[34:35], v[38:39]
	v_lshlrev_b32_e32 v38, 16, v83
	v_cvt_pk_bf16_f32 v34, v34, v35
	v_add_f32_e32 v35, v36, v40
	v_mul_f32_e32 v35, 0xbfb8aa3b, v35
	v_exp_f32_e32 v36, v35
	v_add_f32_e32 v35, v37, v41
	v_mul_f32_e32 v35, 0xbfb8aa3b, v35
	v_exp_f32_e32 v37, v35
	v_and_b32_e32 v39, 0xffff0000, v83
	v_pk_add_f32 v[36:37], v[36:37], 1.0 op_sel_hi:[1,0]
	s_nop 0
	v_rcp_f32_e32 v37, v37
	v_rcp_f32_e32 v36, v36
	s_nop 0
	v_pk_mul_f32 v[36:37], v[36:37], v[38:39]
	s_nop 0
	v_cvt_pk_bf16_f32 v35, v36, v37
	global_store_dwordx2 v[50:51], v[34:35], off
	ds_read_b128 v[38:41], v85 offset:8448
	ds_read_b128 v[160:163], v85 offset:8512
	s_waitcnt lgkmcnt(1)
	v_mfma_f32_16x16x32_bf16 v[38:41], v[38:41], v[30:33], 0
	s_waitcnt lgkmcnt(0)
	v_mfma_f32_16x16x32_bf16 v[38:41], v[160:163], v[26:29], v[38:41]
	ds_read_b128 v[160:163], v85 offset:8576
	s_waitcnt lgkmcnt(0)
	v_mfma_f32_16x16x32_bf16 v[38:41], v[160:163], v[22:25], v[38:41]
	ds_read_b128 v[160:163], v85 offset:8640
	s_waitcnt lgkmcnt(0)
	v_mfma_f32_16x16x32_bf16 v[38:41], v[160:163], v[18:21], v[38:41]
	ds_read_b128 v[160:163], v85 offset:8704
	s_waitcnt lgkmcnt(0)
	v_mfma_f32_16x16x32_bf16 v[38:41], v[160:163], v[14:17], v[38:41]
	ds_read_b128 v[160:163], v85 offset:8768
	s_waitcnt lgkmcnt(0)
	v_mfma_f32_16x16x32_bf16 v[38:41], v[160:163], v[10:13], v[38:41]
	ds_read_b128 v[160:163], v85 offset:8832
	s_waitcnt lgkmcnt(0)
	v_mfma_f32_16x16x32_bf16 v[38:41], v[160:163], v[6:9], v[38:41]
	ds_read_b128 v[160:163], v85 offset:8896
	s_waitcnt lgkmcnt(0)
	v_mfma_f32_16x16x32_bf16 v[38:41], v[160:163], v[2:5], v[38:41]
	s_nop 0
	s_nop 6
	v_add_f32_e32 v34, v164, v38
	v_add_f32_e32 v35, v165, v39
	v_mul_f32_e32 v34, 0xbfb8aa3b, v34
	v_mul_f32_e32 v35, 0xbfb8aa3b, v35
	v_exp_f32_e32 v34, v34
	v_exp_f32_e32 v35, v35
	v_lshlrev_b32_e32 v38, 16, v80
	v_and_b32_e32 v39, 0xffff0000, v80
	v_pk_add_f32 v[34:35], v[34:35], 1.0 op_sel_hi:[1,0]
	s_nop 0
	v_rcp_f32_e32 v35, v35
	v_rcp_f32_e32 v34, v34
	s_nop 0
	v_pk_mul_f32 v[34:35], v[34:35], v[38:39]
	v_lshlrev_b32_e32 v38, 16, v81
	v_cvt_pk_bf16_f32 v34, v34, v35
	v_add_f32_e32 v35, v166, v40
	v_mul_f32_e32 v35, 0xbfb8aa3b, v35
	v_exp_f32_e32 v36, v35
	v_add_f32_e32 v35, v167, v41
	v_mul_f32_e32 v35, 0xbfb8aa3b, v35
	v_exp_f32_e32 v37, v35
	v_and_b32_e32 v39, 0xffff0000, v81
	v_pk_add_f32 v[36:37], v[36:37], 1.0 op_sel_hi:[1,0]
	s_nop 0
	v_rcp_f32_e32 v37, v37
	v_rcp_f32_e32 v36, v36
	s_nop 0
	v_pk_mul_f32 v[36:37], v[36:37], v[38:39]
	s_nop 0
	v_cvt_pk_bf16_f32 v35, v36, v37
	global_store_dwordx2 v[50:51], v[34:35], off offset:32
	ds_read_b128 v[38:41], v85 offset:16896
	ds_read_b128 v[80:83], v85 offset:16960
	s_waitcnt lgkmcnt(1)
	v_mfma_f32_16x16x32_bf16 v[38:41], v[38:41], v[30:33], 0
	s_waitcnt lgkmcnt(0)
	v_mfma_f32_16x16x32_bf16 v[38:41], v[80:83], v[26:29], v[38:41]
	ds_read_b128 v[80:83], v85 offset:17024
	s_waitcnt lgkmcnt(0)
	v_mfma_f32_16x16x32_bf16 v[38:41], v[80:83], v[22:25], v[38:41]
	ds_read_b128 v[80:83], v85 offset:17088
	s_waitcnt lgkmcnt(0)
	v_mfma_f32_16x16x32_bf16 v[38:41], v[80:83], v[18:21], v[38:41]
	ds_read_b128 v[80:83], v85 offset:17152
	s_waitcnt lgkmcnt(0)
	v_mfma_f32_16x16x32_bf16 v[38:41], v[80:83], v[14:17], v[38:41]
	ds_read_b128 v[80:83], v85 offset:17216
	s_waitcnt lgkmcnt(0)
	v_mfma_f32_16x16x32_bf16 v[38:41], v[80:83], v[10:13], v[38:41]
	ds_read_b128 v[80:83], v85 offset:17280
	s_waitcnt lgkmcnt(0)
	v_mfma_f32_16x16x32_bf16 v[38:41], v[80:83], v[6:9], v[38:41]
	ds_read_b128 v[80:83], v85 offset:17344
	s_waitcnt lgkmcnt(0)
	v_mfma_f32_16x16x32_bf16 v[38:41], v[80:83], v[2:5], v[38:41]
	s_nop 0
	s_nop 6
	v_add_f32_e32 v34, v168, v38
	v_add_f32_e32 v35, v169, v39
	v_mul_f32_e32 v34, 0xbfb8aa3b, v34
	v_mul_f32_e32 v35, 0xbfb8aa3b, v35
	v_exp_f32_e32 v34, v34
	v_exp_f32_e32 v35, v35
	v_lshlrev_b32_e32 v38, 16, v78
	v_and_b32_e32 v39, 0xffff0000, v78
	v_pk_add_f32 v[34:35], v[34:35], 1.0 op_sel_hi:[1,0]
	s_nop 0
	v_rcp_f32_e32 v35, v35
	v_rcp_f32_e32 v34, v34
	s_nop 0
	v_pk_mul_f32 v[34:35], v[34:35], v[38:39]
	v_lshlrev_b32_e32 v38, 16, v79
	v_cvt_pk_bf16_f32 v34, v34, v35
	v_add_f32_e32 v35, v170, v40
	v_mul_f32_e32 v35, 0xbfb8aa3b, v35
	v_exp_f32_e32 v36, v35
	v_add_f32_e32 v35, v171, v41
	v_mul_f32_e32 v35, 0xbfb8aa3b, v35
	v_exp_f32_e32 v37, v35
	v_and_b32_e32 v39, 0xffff0000, v79
	v_pk_add_f32 v[36:37], v[36:37], 1.0 op_sel_hi:[1,0]
	s_nop 0
	v_rcp_f32_e32 v37, v37
	v_rcp_f32_e32 v36, v36
	s_nop 0
	v_pk_mul_f32 v[36:37], v[36:37], v[38:39]
	s_nop 0
	v_cvt_pk_bf16_f32 v35, v36, v37
	global_store_dwordx2 v[50:51], v[34:35], off offset:64
	ds_read_b128 v[38:41], v85 offset:25344
	ds_read_b128 v[78:81], v85 offset:25408
	s_waitcnt lgkmcnt(1)
	v_mfma_f32_16x16x32_bf16 v[38:41], v[38:41], v[30:33], 0
	s_waitcnt lgkmcnt(0)
	v_mfma_f32_16x16x32_bf16 v[38:41], v[78:81], v[26:29], v[38:41]
	ds_read_b128 v[78:81], v85 offset:25472
	s_waitcnt lgkmcnt(0)
	v_mfma_f32_16x16x32_bf16 v[38:41], v[78:81], v[22:25], v[38:41]
	ds_read_b128 v[78:81], v85 offset:25536
	s_waitcnt lgkmcnt(0)
	v_mfma_f32_16x16x32_bf16 v[38:41], v[78:81], v[18:21], v[38:41]
	ds_read_b128 v[78:81], v85 offset:25600
	s_waitcnt lgkmcnt(0)
	v_mfma_f32_16x16x32_bf16 v[38:41], v[78:81], v[14:17], v[38:41]
	ds_read_b128 v[78:81], v85 offset:25664
	s_waitcnt lgkmcnt(0)
	v_mfma_f32_16x16x32_bf16 v[38:41], v[78:81], v[10:13], v[38:41]
	ds_read_b128 v[78:81], v85 offset:25728
	s_waitcnt lgkmcnt(0)
	v_mfma_f32_16x16x32_bf16 v[38:41], v[78:81], v[6:9], v[38:41]
	ds_read_b128 v[78:81], v85 offset:25792
	s_waitcnt lgkmcnt(0)
	v_mfma_f32_16x16x32_bf16 v[38:41], v[78:81], v[2:5], v[38:41]
	s_nop 0
	s_nop 6
	v_add_f32_e32 v34, v172, v38
	v_add_f32_e32 v35, v173, v39
	v_mul_f32_e32 v34, 0xbfb8aa3b, v34
	v_mul_f32_e32 v35, 0xbfb8aa3b, v35
	v_exp_f32_e32 v34, v34
	v_exp_f32_e32 v35, v35
	v_lshlrev_b32_e32 v38, 16, v76
	v_and_b32_e32 v39, 0xffff0000, v76
	v_pk_add_f32 v[34:35], v[34:35], 1.0 op_sel_hi:[1,0]
	s_nop 0
	v_rcp_f32_e32 v35, v35
	v_rcp_f32_e32 v34, v34
	s_nop 0
	v_pk_mul_f32 v[34:35], v[34:35], v[38:39]
	v_lshlrev_b32_e32 v38, 16, v77
	v_cvt_pk_bf16_f32 v34, v34, v35
	v_add_f32_e32 v35, v174, v40
	v_mul_f32_e32 v35, 0xbfb8aa3b, v35
	v_exp_f32_e32 v36, v35
	v_add_f32_e32 v35, v175, v41
	v_mul_f32_e32 v35, 0xbfb8aa3b, v35
	v_exp_f32_e32 v37, v35
	v_and_b32_e32 v39, 0xffff0000, v77
	v_pk_add_f32 v[36:37], v[36:37], 1.0 op_sel_hi:[1,0]
	s_nop 0
	v_rcp_f32_e32 v37, v37
	v_rcp_f32_e32 v36, v36
	s_nop 0
	v_pk_mul_f32 v[36:37], v[36:37], v[38:39]
	s_nop 0
	v_cvt_pk_bf16_f32 v35, v36, v37
	global_store_dwordx2 v[50:51], v[34:35], off offset:96
	ds_read_b128 v[38:41], v85 offset:33792
	ds_read_b128 v[76:79], v85 offset:33856
	s_waitcnt lgkmcnt(1)
	v_mfma_f32_16x16x32_bf16 v[38:41], v[38:41], v[30:33], 0
	s_waitcnt lgkmcnt(0)
	v_mfma_f32_16x16x32_bf16 v[38:41], v[76:79], v[26:29], v[38:41]
	ds_read_b128 v[76:79], v85 offset:33920
	s_waitcnt lgkmcnt(0)
	v_mfma_f32_16x16x32_bf16 v[38:41], v[76:79], v[22:25], v[38:41]
	ds_read_b128 v[76:79], v85 offset:33984
	s_waitcnt lgkmcnt(0)
	v_mfma_f32_16x16x32_bf16 v[38:41], v[76:79], v[18:21], v[38:41]
	ds_read_b128 v[76:79], v85 offset:34048
	s_waitcnt lgkmcnt(0)
	v_mfma_f32_16x16x32_bf16 v[38:41], v[76:79], v[14:17], v[38:41]
	ds_read_b128 v[76:79], v85 offset:34112
	s_waitcnt lgkmcnt(0)
	v_mfma_f32_16x16x32_bf16 v[38:41], v[76:79], v[10:13], v[38:41]
	ds_read_b128 v[76:79], v85 offset:34176
	s_waitcnt lgkmcnt(0)
	v_mfma_f32_16x16x32_bf16 v[38:41], v[76:79], v[6:9], v[38:41]
	ds_read_b128 v[76:79], v85 offset:34240
	s_waitcnt lgkmcnt(0)
	v_mfma_f32_16x16x32_bf16 v[38:41], v[76:79], v[2:5], v[38:41]
	s_nop 0
	s_nop 6
	v_add_f32_e32 v34, v176, v38
	v_add_f32_e32 v35, v177, v39
	v_mul_f32_e32 v34, 0xbfb8aa3b, v34
	v_mul_f32_e32 v35, 0xbfb8aa3b, v35
	v_exp_f32_e32 v34, v34
	v_exp_f32_e32 v35, v35
	v_lshlrev_b32_e32 v38, 16, v74
	v_and_b32_e32 v39, 0xffff0000, v74
	v_pk_add_f32 v[34:35], v[34:35], 1.0 op_sel_hi:[1,0]
	s_nop 0
	v_rcp_f32_e32 v35, v35
	v_rcp_f32_e32 v34, v34
	s_nop 0
	v_pk_mul_f32 v[34:35], v[34:35], v[38:39]
	v_lshlrev_b32_e32 v38, 16, v75
	v_cvt_pk_bf16_f32 v34, v34, v35
	v_add_f32_e32 v35, v178, v40
	v_mul_f32_e32 v35, 0xbfb8aa3b, v35
	v_exp_f32_e32 v36, v35
	v_add_f32_e32 v35, v179, v41
	v_mul_f32_e32 v35, 0xbfb8aa3b, v35
	v_exp_f32_e32 v37, v35
	v_and_b32_e32 v39, 0xffff0000, v75
	v_pk_add_f32 v[36:37], v[36:37], 1.0 op_sel_hi:[1,0]
	s_nop 0
	v_rcp_f32_e32 v37, v37
	v_rcp_f32_e32 v36, v36
	s_nop 0
	v_pk_mul_f32 v[36:37], v[36:37], v[38:39]
	s_nop 0
	v_cvt_pk_bf16_f32 v35, v36, v37
	global_store_dwordx2 v[50:51], v[34:35], off offset:128
	ds_read_b128 v[38:41], v85 offset:42240
	ds_read_b128 v[74:77], v85 offset:42304
	s_waitcnt lgkmcnt(1)
	v_mfma_f32_16x16x32_bf16 v[38:41], v[38:41], v[30:33], 0
	s_waitcnt lgkmcnt(0)
	v_mfma_f32_16x16x32_bf16 v[38:41], v[74:77], v[26:29], v[38:41]
	ds_read_b128 v[74:77], v85 offset:42368
	s_waitcnt lgkmcnt(0)
	v_mfma_f32_16x16x32_bf16 v[38:41], v[74:77], v[22:25], v[38:41]
	ds_read_b128 v[74:77], v85 offset:42432
	s_waitcnt lgkmcnt(0)
	v_mfma_f32_16x16x32_bf16 v[38:41], v[74:77], v[18:21], v[38:41]
	ds_read_b128 v[74:77], v85 offset:42496
	s_waitcnt lgkmcnt(0)
	v_mfma_f32_16x16x32_bf16 v[38:41], v[74:77], v[14:17], v[38:41]
	ds_read_b128 v[74:77], v85 offset:42560
	s_waitcnt lgkmcnt(0)
	v_mfma_f32_16x16x32_bf16 v[38:41], v[74:77], v[10:13], v[38:41]
	ds_read_b128 v[74:77], v85 offset:42624
	s_waitcnt lgkmcnt(0)
	v_mfma_f32_16x16x32_bf16 v[38:41], v[74:77], v[6:9], v[38:41]
	ds_read_b128 v[74:77], v85 offset:42688
	s_waitcnt lgkmcnt(0)
	v_mfma_f32_16x16x32_bf16 v[38:41], v[74:77], v[2:5], v[38:41]
	s_nop 0
	s_nop 6
	v_add_f32_e32 v34, v180, v38
	v_add_f32_e32 v35, v181, v39
	v_mul_f32_e32 v34, 0xbfb8aa3b, v34
	v_mul_f32_e32 v35, 0xbfb8aa3b, v35
	v_exp_f32_e32 v34, v34
	v_exp_f32_e32 v35, v35
	v_lshlrev_b32_e32 v38, 16, v72
	v_and_b32_e32 v39, 0xffff0000, v72
	v_pk_add_f32 v[34:35], v[34:35], 1.0 op_sel_hi:[1,0]
	s_nop 0
	v_rcp_f32_e32 v35, v35
	v_rcp_f32_e32 v34, v34
	s_nop 0
	v_pk_mul_f32 v[34:35], v[34:35], v[38:39]
	v_lshlrev_b32_e32 v38, 16, v73
	v_cvt_pk_bf16_f32 v34, v34, v35
	v_add_f32_e32 v35, v182, v40
	v_mul_f32_e32 v35, 0xbfb8aa3b, v35
	v_exp_f32_e32 v36, v35
	v_add_f32_e32 v35, v183, v41
	v_mul_f32_e32 v35, 0xbfb8aa3b, v35
	v_exp_f32_e32 v37, v35
	v_and_b32_e32 v39, 0xffff0000, v73
	v_pk_add_f32 v[36:37], v[36:37], 1.0 op_sel_hi:[1,0]
	s_nop 0
	v_rcp_f32_e32 v37, v37
	v_rcp_f32_e32 v36, v36
	s_nop 0
	v_pk_mul_f32 v[36:37], v[36:37], v[38:39]
	s_nop 0
	v_cvt_pk_bf16_f32 v35, v36, v37
	global_store_dwordx2 v[50:51], v[34:35], off offset:160
	ds_read_b128 v[38:41], v85 offset:50688
	ds_read_b128 v[72:75], v85 offset:50752
	s_waitcnt lgkmcnt(1)
	v_mfma_f32_16x16x32_bf16 v[38:41], v[38:41], v[30:33], 0
	s_waitcnt lgkmcnt(0)
	v_mfma_f32_16x16x32_bf16 v[38:41], v[72:75], v[26:29], v[38:41]
	ds_read_b128 v[72:75], v85 offset:50816
	s_waitcnt lgkmcnt(0)
	v_mfma_f32_16x16x32_bf16 v[38:41], v[72:75], v[22:25], v[38:41]
	ds_read_b128 v[72:75], v85 offset:50880
	s_waitcnt lgkmcnt(0)
	v_mfma_f32_16x16x32_bf16 v[38:41], v[72:75], v[18:21], v[38:41]
	ds_read_b128 v[72:75], v85 offset:50944
	s_waitcnt lgkmcnt(0)
	v_mfma_f32_16x16x32_bf16 v[38:41], v[72:75], v[14:17], v[38:41]
	ds_read_b128 v[72:75], v85 offset:51008
	s_waitcnt lgkmcnt(0)
	v_mfma_f32_16x16x32_bf16 v[38:41], v[72:75], v[10:13], v[38:41]
	ds_read_b128 v[72:75], v85 offset:51072
	s_waitcnt lgkmcnt(0)
	v_mfma_f32_16x16x32_bf16 v[38:41], v[72:75], v[6:9], v[38:41]
	ds_read_b128 v[72:75], v85 offset:51136
	s_waitcnt lgkmcnt(0)
	v_mfma_f32_16x16x32_bf16 v[38:41], v[72:75], v[2:5], v[38:41]
	s_nop 0
	s_nop 6
	v_add_f32_e32 v34, v184, v38
	v_add_f32_e32 v35, v185, v39
	v_mul_f32_e32 v34, 0xbfb8aa3b, v34
	v_mul_f32_e32 v35, 0xbfb8aa3b, v35
	v_exp_f32_e32 v34, v34
	v_exp_f32_e32 v35, v35
	v_lshlrev_b32_e32 v38, 16, v70
	v_and_b32_e32 v39, 0xffff0000, v70
	v_pk_add_f32 v[34:35], v[34:35], 1.0 op_sel_hi:[1,0]
	s_nop 0
	v_rcp_f32_e32 v35, v35
	v_rcp_f32_e32 v34, v34
	s_nop 0
	v_pk_mul_f32 v[34:35], v[34:35], v[38:39]
	v_lshlrev_b32_e32 v38, 16, v71
	v_cvt_pk_bf16_f32 v34, v34, v35
	v_add_f32_e32 v35, v186, v40
	v_mul_f32_e32 v35, 0xbfb8aa3b, v35
	v_exp_f32_e32 v36, v35
	v_add_f32_e32 v35, v187, v41
	v_mul_f32_e32 v35, 0xbfb8aa3b, v35
	v_exp_f32_e32 v37, v35
	v_and_b32_e32 v39, 0xffff0000, v71
	v_pk_add_f32 v[36:37], v[36:37], 1.0 op_sel_hi:[1,0]
	s_nop 0
	v_rcp_f32_e32 v37, v37
	v_rcp_f32_e32 v36, v36
	s_nop 0
	v_pk_mul_f32 v[36:37], v[36:37], v[38:39]
	s_nop 0
	v_cvt_pk_bf16_f32 v35, v36, v37
	global_store_dwordx2 v[50:51], v[34:35], off offset:192
	ds_read_b128 v[38:41], v85 offset:59136
	ds_read_b128 v[70:73], v85 offset:59200
	s_waitcnt lgkmcnt(1)
	v_mfma_f32_16x16x32_bf16 v[38:41], v[38:41], v[30:33], 0
	s_waitcnt lgkmcnt(0)
	v_mfma_f32_16x16x32_bf16 v[38:41], v[70:73], v[26:29], v[38:41]
	ds_read_b128 v[70:73], v85 offset:59264
	s_waitcnt lgkmcnt(0)
	v_mfma_f32_16x16x32_bf16 v[38:41], v[70:73], v[22:25], v[38:41]
	ds_read_b128 v[70:73], v85 offset:59328
	s_waitcnt lgkmcnt(0)
	v_mfma_f32_16x16x32_bf16 v[38:41], v[70:73], v[18:21], v[38:41]
	ds_read_b128 v[70:73], v85 offset:59392
	s_waitcnt lgkmcnt(0)
	v_mfma_f32_16x16x32_bf16 v[38:41], v[70:73], v[14:17], v[38:41]
	ds_read_b128 v[70:73], v85 offset:59456
	s_waitcnt lgkmcnt(0)
	v_mfma_f32_16x16x32_bf16 v[38:41], v[70:73], v[10:13], v[38:41]
	ds_read_b128 v[70:73], v85 offset:59520
	s_waitcnt lgkmcnt(0)
	v_mfma_f32_16x16x32_bf16 v[38:41], v[70:73], v[6:9], v[38:41]
	ds_read_b128 v[70:73], v85 offset:59584
	s_waitcnt lgkmcnt(0)
	v_mfma_f32_16x16x32_bf16 v[38:41], v[70:73], v[2:5], v[38:41]
	s_nop 0
	s_nop 6
	v_add_f32_e32 v34, v188, v38
	v_add_f32_e32 v35, v189, v39
	v_mul_f32_e32 v34, 0xbfb8aa3b, v34
	v_mul_f32_e32 v35, 0xbfb8aa3b, v35
	v_exp_f32_e32 v34, v34
	v_exp_f32_e32 v35, v35
	v_lshlrev_b32_e32 v38, 16, v68
	v_and_b32_e32 v39, 0xffff0000, v68
	v_pk_add_f32 v[34:35], v[34:35], 1.0 op_sel_hi:[1,0]
	s_nop 0
	v_rcp_f32_e32 v35, v35
	v_rcp_f32_e32 v34, v34
	s_nop 0
	v_pk_mul_f32 v[34:35], v[34:35], v[38:39]
	v_lshlrev_b32_e32 v38, 16, v69
	v_cvt_pk_bf16_f32 v34, v34, v35
	v_add_f32_e32 v35, v190, v40
	v_mul_f32_e32 v35, 0xbfb8aa3b, v35
	v_exp_f32_e32 v36, v35
	v_add_f32_e32 v35, v191, v41
	v_mul_f32_e32 v35, 0xbfb8aa3b, v35
	v_exp_f32_e32 v37, v35
	v_and_b32_e32 v39, 0xffff0000, v69
	v_pk_add_f32 v[36:37], v[36:37], 1.0 op_sel_hi:[1,0]
	s_nop 0
	v_rcp_f32_e32 v37, v37
	v_rcp_f32_e32 v36, v36
	s_nop 0
	v_pk_mul_f32 v[36:37], v[36:37], v[38:39]
	s_nop 0
	v_cvt_pk_bf16_f32 v35, v36, v37
	global_store_dwordx2 v[50:51], v[34:35], off offset:224
	ds_read_b128 v[38:41], v86
	ds_read_b128 v[68:71], v87
	s_waitcnt lgkmcnt(1)
	v_mfma_f32_16x16x32_bf16 v[38:41], v[38:41], v[30:33], 0
	s_waitcnt lgkmcnt(0)
	v_mfma_f32_16x16x32_bf16 v[38:41], v[68:71], v[26:29], v[38:41]
	ds_read_b128 v[68:71], v88
	s_waitcnt lgkmcnt(0)
	v_mfma_f32_16x16x32_bf16 v[38:41], v[68:71], v[22:25], v[38:41]
	ds_read_b128 v[68:71], v89
	s_waitcnt lgkmcnt(0)
	v_mfma_f32_16x16x32_bf16 v[38:41], v[68:71], v[18:21], v[38:41]
	ds_read_b128 v[68:71], v90
	s_waitcnt lgkmcnt(0)
	v_mfma_f32_16x16x32_bf16 v[38:41], v[68:71], v[14:17], v[38:41]
	ds_read_b128 v[68:71], v91
	s_waitcnt lgkmcnt(0)
	v_mfma_f32_16x16x32_bf16 v[38:41], v[68:71], v[10:13], v[38:41]
	ds_read_b128 v[68:71], v92
	s_waitcnt lgkmcnt(0)
	v_mfma_f32_16x16x32_bf16 v[38:41], v[68:71], v[6:9], v[38:41]
	ds_read_b128 v[68:71], v93
	s_waitcnt lgkmcnt(0)
	v_mfma_f32_16x16x32_bf16 v[38:41], v[68:71], v[2:5], v[38:41]
	s_nop 0
	s_nop 6
	v_add_f32_e32 v34, v192, v38
	v_add_f32_e32 v35, v193, v39
	v_mul_f32_e32 v34, 0xbfb8aa3b, v34
	v_mul_f32_e32 v35, 0xbfb8aa3b, v35
	v_exp_f32_e32 v34, v34
	v_exp_f32_e32 v35, v35
	v_lshlrev_b32_e32 v38, 16, v66
	v_and_b32_e32 v39, 0xffff0000, v66
	v_pk_add_f32 v[34:35], v[34:35], 1.0 op_sel_hi:[1,0]
	s_nop 0
	v_rcp_f32_e32 v35, v35
	v_rcp_f32_e32 v34, v34
	s_nop 0
	v_pk_mul_f32 v[34:35], v[34:35], v[38:39]
	v_lshlrev_b32_e32 v38, 16, v67
	v_cvt_pk_bf16_f32 v34, v34, v35
	v_add_f32_e32 v35, v194, v40
	v_mul_f32_e32 v35, 0xbfb8aa3b, v35
	v_exp_f32_e32 v36, v35
	v_add_f32_e32 v35, v195, v41
	v_mul_f32_e32 v35, 0xbfb8aa3b, v35
	v_exp_f32_e32 v37, v35
	v_and_b32_e32 v39, 0xffff0000, v67
	v_pk_add_f32 v[36:37], v[36:37], 1.0 op_sel_hi:[1,0]
	s_nop 0
	v_rcp_f32_e32 v37, v37
	v_rcp_f32_e32 v36, v36
	s_nop 0
	v_pk_mul_f32 v[36:37], v[36:37], v[38:39]
	s_nop 0
	v_cvt_pk_bf16_f32 v35, v36, v37
	global_store_dwordx2 v[50:51], v[34:35], off offset:256
	ds_read_b128 v[38:41], v94
	ds_read_b128 v[66:69], v95
	s_waitcnt lgkmcnt(1)
	v_mfma_f32_16x16x32_bf16 v[38:41], v[38:41], v[30:33], 0
	s_waitcnt lgkmcnt(0)
	v_mfma_f32_16x16x32_bf16 v[38:41], v[66:69], v[26:29], v[38:41]
	ds_read_b128 v[66:69], v96
	s_waitcnt lgkmcnt(0)
	v_mfma_f32_16x16x32_bf16 v[38:41], v[66:69], v[22:25], v[38:41]
	ds_read_b128 v[66:69], v97
	s_waitcnt lgkmcnt(0)
	v_mfma_f32_16x16x32_bf16 v[38:41], v[66:69], v[18:21], v[38:41]
	ds_read_b128 v[66:69], v98
	s_waitcnt lgkmcnt(0)
	v_mfma_f32_16x16x32_bf16 v[38:41], v[66:69], v[14:17], v[38:41]
	ds_read_b128 v[66:69], v99
	s_waitcnt lgkmcnt(0)
	v_mfma_f32_16x16x32_bf16 v[38:41], v[66:69], v[10:13], v[38:41]
	ds_read_b128 v[66:69], v100
	s_waitcnt lgkmcnt(0)
	v_mfma_f32_16x16x32_bf16 v[38:41], v[66:69], v[6:9], v[38:41]
	ds_read_b128 v[66:69], v101
	s_waitcnt lgkmcnt(0)
	v_mfma_f32_16x16x32_bf16 v[38:41], v[66:69], v[2:5], v[38:41]
	s_nop 0
	s_nop 6
	v_add_f32_e32 v34, v196, v38
	v_add_f32_e32 v35, v197, v39
	v_mul_f32_e32 v34, 0xbfb8aa3b, v34
	v_mul_f32_e32 v35, 0xbfb8aa3b, v35
	v_exp_f32_e32 v34, v34
	v_exp_f32_e32 v35, v35
	v_lshlrev_b32_e32 v38, 16, v64
	v_and_b32_e32 v39, 0xffff0000, v64
	v_pk_add_f32 v[34:35], v[34:35], 1.0 op_sel_hi:[1,0]
	s_nop 0
	v_rcp_f32_e32 v35, v35
	v_rcp_f32_e32 v34, v34
	s_nop 0
	v_pk_mul_f32 v[34:35], v[34:35], v[38:39]
	v_lshlrev_b32_e32 v38, 16, v65
	v_cvt_pk_bf16_f32 v34, v34, v35
	v_add_f32_e32 v35, v198, v40
	v_mul_f32_e32 v35, 0xbfb8aa3b, v35
	v_exp_f32_e32 v36, v35
	v_add_f32_e32 v35, v199, v41
	v_mul_f32_e32 v35, 0xbfb8aa3b, v35
	v_exp_f32_e32 v37, v35
	v_and_b32_e32 v39, 0xffff0000, v65
	v_pk_add_f32 v[36:37], v[36:37], 1.0 op_sel_hi:[1,0]
	s_nop 0
	v_rcp_f32_e32 v37, v37
	v_rcp_f32_e32 v36, v36
	s_nop 0
	v_pk_mul_f32 v[36:37], v[36:37], v[38:39]
	s_nop 0
	v_cvt_pk_bf16_f32 v35, v36, v37
	global_store_dwordx2 v[50:51], v[34:35], off offset:288
	ds_read_b128 v[38:41], v102
	ds_read_b128 v[64:67], v103
	s_waitcnt lgkmcnt(1)
	v_mfma_f32_16x16x32_bf16 v[38:41], v[38:41], v[30:33], 0
	s_waitcnt lgkmcnt(0)
	v_mfma_f32_16x16x32_bf16 v[38:41], v[64:67], v[26:29], v[38:41]
	ds_read_b128 v[64:67], v104
	s_waitcnt lgkmcnt(0)
	v_mfma_f32_16x16x32_bf16 v[38:41], v[64:67], v[22:25], v[38:41]
	ds_read_b128 v[64:67], v105
	s_waitcnt lgkmcnt(0)
	v_mfma_f32_16x16x32_bf16 v[38:41], v[64:67], v[18:21], v[38:41]
	ds_read_b128 v[64:67], v106
	s_waitcnt lgkmcnt(0)
	v_mfma_f32_16x16x32_bf16 v[38:41], v[64:67], v[14:17], v[38:41]
	ds_read_b128 v[64:67], v107
	s_waitcnt lgkmcnt(0)
	v_mfma_f32_16x16x32_bf16 v[38:41], v[64:67], v[10:13], v[38:41]
	ds_read_b128 v[64:67], v108
	s_waitcnt lgkmcnt(0)
	v_mfma_f32_16x16x32_bf16 v[38:41], v[64:67], v[6:9], v[38:41]
	ds_read_b128 v[64:67], v109
	s_waitcnt lgkmcnt(0)
	v_mfma_f32_16x16x32_bf16 v[38:41], v[64:67], v[2:5], v[38:41]
	s_nop 0
	s_nop 6
	v_add_f32_e32 v34, v200, v38
	v_add_f32_e32 v35, v201, v39
	v_mul_f32_e32 v34, 0xbfb8aa3b, v34
	v_mul_f32_e32 v35, 0xbfb8aa3b, v35
	v_exp_f32_e32 v34, v34
	v_exp_f32_e32 v35, v35
	v_lshlrev_b32_e32 v38, 16, v62
	v_and_b32_e32 v39, 0xffff0000, v62
	v_pk_add_f32 v[34:35], v[34:35], 1.0 op_sel_hi:[1,0]
	s_nop 0
	v_rcp_f32_e32 v35, v35
	v_rcp_f32_e32 v34, v34
	s_nop 0
	v_pk_mul_f32 v[34:35], v[34:35], v[38:39]
	v_lshlrev_b32_e32 v38, 16, v63
	v_cvt_pk_bf16_f32 v34, v34, v35
	v_add_f32_e32 v35, v202, v40
	v_mul_f32_e32 v35, 0xbfb8aa3b, v35
	v_exp_f32_e32 v36, v35
	v_add_f32_e32 v35, v203, v41
	v_mul_f32_e32 v35, 0xbfb8aa3b, v35
	v_exp_f32_e32 v37, v35
	v_and_b32_e32 v39, 0xffff0000, v63
	v_pk_add_f32 v[36:37], v[36:37], 1.0 op_sel_hi:[1,0]
	s_nop 0
	v_rcp_f32_e32 v37, v37
	v_rcp_f32_e32 v36, v36
	s_nop 0
	v_pk_mul_f32 v[36:37], v[36:37], v[38:39]
	s_nop 0
	v_cvt_pk_bf16_f32 v35, v36, v37
	global_store_dwordx2 v[50:51], v[34:35], off offset:320
	ds_read_b128 v[38:41], v110
	ds_read_b128 v[62:65], v111
	s_waitcnt lgkmcnt(1)
	v_mfma_f32_16x16x32_bf16 v[38:41], v[38:41], v[30:33], 0
	s_waitcnt lgkmcnt(0)
	v_mfma_f32_16x16x32_bf16 v[38:41], v[62:65], v[26:29], v[38:41]
	ds_read_b128 v[62:65], v112
	s_waitcnt lgkmcnt(0)
	v_mfma_f32_16x16x32_bf16 v[38:41], v[62:65], v[22:25], v[38:41]
	ds_read_b128 v[62:65], v113
	s_waitcnt lgkmcnt(0)
	v_mfma_f32_16x16x32_bf16 v[38:41], v[62:65], v[18:21], v[38:41]
	ds_read_b128 v[62:65], v114
	s_waitcnt lgkmcnt(0)
	v_mfma_f32_16x16x32_bf16 v[38:41], v[62:65], v[14:17], v[38:41]
	ds_read_b128 v[62:65], v115
	s_waitcnt lgkmcnt(0)
	v_mfma_f32_16x16x32_bf16 v[38:41], v[62:65], v[10:13], v[38:41]
	ds_read_b128 v[62:65], v116
	s_waitcnt lgkmcnt(0)
	v_mfma_f32_16x16x32_bf16 v[38:41], v[62:65], v[6:9], v[38:41]
	ds_read_b128 v[62:65], v117
	s_waitcnt lgkmcnt(0)
	v_mfma_f32_16x16x32_bf16 v[38:41], v[62:65], v[2:5], v[38:41]
	s_nop 0
	s_nop 6
	v_add_f32_e32 v34, v234, v38
	v_add_f32_e32 v35, v235, v39
	v_mul_f32_e32 v34, 0xbfb8aa3b, v34
	v_mul_f32_e32 v35, 0xbfb8aa3b, v35
	v_exp_f32_e32 v34, v34
	v_exp_f32_e32 v35, v35
	v_lshlrev_b32_e32 v38, 16, v60
	v_and_b32_e32 v39, 0xffff0000, v60
	v_pk_add_f32 v[34:35], v[34:35], 1.0 op_sel_hi:[1,0]
	s_nop 0
	v_rcp_f32_e32 v35, v35
	v_rcp_f32_e32 v34, v34
	s_nop 0
	v_pk_mul_f32 v[34:35], v[34:35], v[38:39]
	v_lshlrev_b32_e32 v38, 16, v61
	v_cvt_pk_bf16_f32 v34, v34, v35
	v_add_f32_e32 v35, v236, v40
	v_mul_f32_e32 v35, 0xbfb8aa3b, v35
	v_exp_f32_e32 v36, v35
	v_add_f32_e32 v35, v237, v41
	v_mul_f32_e32 v35, 0xbfb8aa3b, v35
	v_exp_f32_e32 v37, v35
	v_and_b32_e32 v39, 0xffff0000, v61
	v_pk_add_f32 v[36:37], v[36:37], 1.0 op_sel_hi:[1,0]
	s_nop 0
	v_rcp_f32_e32 v37, v37
	v_rcp_f32_e32 v36, v36
	s_nop 0
	v_pk_mul_f32 v[36:37], v[36:37], v[38:39]
	s_nop 0
	v_cvt_pk_bf16_f32 v35, v36, v37
	global_store_dwordx2 v[50:51], v[34:35], off offset:352
	ds_read_b128 v[38:41], v118
	ds_read_b128 v[60:63], v119
	s_waitcnt lgkmcnt(1)
	v_mfma_f32_16x16x32_bf16 v[38:41], v[38:41], v[30:33], 0
	s_waitcnt lgkmcnt(0)
	v_mfma_f32_16x16x32_bf16 v[38:41], v[60:63], v[26:29], v[38:41]
	ds_read_b128 v[60:63], v120
	s_waitcnt lgkmcnt(0)
	v_mfma_f32_16x16x32_bf16 v[38:41], v[60:63], v[22:25], v[38:41]
	ds_read_b128 v[60:63], v121
	s_waitcnt lgkmcnt(0)
	v_mfma_f32_16x16x32_bf16 v[38:41], v[60:63], v[18:21], v[38:41]
	ds_read_b128 v[60:63], v122
	s_waitcnt lgkmcnt(0)
	v_mfma_f32_16x16x32_bf16 v[38:41], v[60:63], v[14:17], v[38:41]
	ds_read_b128 v[60:63], v123
	s_waitcnt lgkmcnt(0)
	v_mfma_f32_16x16x32_bf16 v[38:41], v[60:63], v[10:13], v[38:41]
	ds_read_b128 v[60:63], v124
	s_waitcnt lgkmcnt(0)
	v_mfma_f32_16x16x32_bf16 v[38:41], v[60:63], v[6:9], v[38:41]
	ds_read_b128 v[60:63], v125
	s_waitcnt lgkmcnt(0)
	v_mfma_f32_16x16x32_bf16 v[38:41], v[60:63], v[2:5], v[38:41]
	s_nop 0
	s_nop 6
	v_add_f32_e32 v34, v238, v38
	v_add_f32_e32 v35, v239, v39
	v_mul_f32_e32 v34, 0xbfb8aa3b, v34
	v_mul_f32_e32 v35, 0xbfb8aa3b, v35
	v_exp_f32_e32 v34, v34
	v_exp_f32_e32 v35, v35
	v_lshlrev_b32_e32 v38, 16, v58
	v_and_b32_e32 v39, 0xffff0000, v58
	v_pk_add_f32 v[34:35], v[34:35], 1.0 op_sel_hi:[1,0]
	s_nop 0
	v_rcp_f32_e32 v35, v35
	v_rcp_f32_e32 v34, v34
	s_nop 0
	v_pk_mul_f32 v[34:35], v[34:35], v[38:39]
	v_lshlrev_b32_e32 v38, 16, v59
	v_cvt_pk_bf16_f32 v34, v34, v35
	v_add_f32_e32 v35, v240, v40
	v_mul_f32_e32 v35, 0xbfb8aa3b, v35
	v_exp_f32_e32 v36, v35
	v_add_f32_e32 v35, v241, v41
	v_mul_f32_e32 v35, 0xbfb8aa3b, v35
	v_exp_f32_e32 v37, v35
	v_and_b32_e32 v39, 0xffff0000, v59
	v_pk_add_f32 v[36:37], v[36:37], 1.0 op_sel_hi:[1,0]
	s_nop 0
	v_rcp_f32_e32 v37, v37
	v_rcp_f32_e32 v36, v36
	s_nop 0
	v_pk_mul_f32 v[36:37], v[36:37], v[38:39]
	s_nop 0
	v_cvt_pk_bf16_f32 v35, v36, v37
	global_store_dwordx2 v[50:51], v[34:35], off offset:384
	ds_read_b128 v[38:41], v126
	ds_read_b128 v[58:61], v127
	s_waitcnt lgkmcnt(1)
	v_mfma_f32_16x16x32_bf16 v[38:41], v[38:41], v[30:33], 0
	s_waitcnt lgkmcnt(0)
	v_mfma_f32_16x16x32_bf16 v[38:41], v[58:61], v[26:29], v[38:41]
	ds_read_b128 v[58:61], v128
	s_waitcnt lgkmcnt(0)
	v_mfma_f32_16x16x32_bf16 v[38:41], v[58:61], v[22:25], v[38:41]
	ds_read_b128 v[58:61], v129
	s_waitcnt lgkmcnt(0)
	v_mfma_f32_16x16x32_bf16 v[38:41], v[58:61], v[18:21], v[38:41]
	ds_read_b128 v[58:61], v130
	s_waitcnt lgkmcnt(0)
	v_mfma_f32_16x16x32_bf16 v[38:41], v[58:61], v[14:17], v[38:41]
	ds_read_b128 v[58:61], v131
	s_waitcnt lgkmcnt(0)
	v_mfma_f32_16x16x32_bf16 v[38:41], v[58:61], v[10:13], v[38:41]
	ds_read_b128 v[58:61], v132
	s_waitcnt lgkmcnt(0)
	v_mfma_f32_16x16x32_bf16 v[38:41], v[58:61], v[6:9], v[38:41]
	ds_read_b128 v[58:61], v133
	s_waitcnt lgkmcnt(0)
	v_mfma_f32_16x16x32_bf16 v[38:41], v[58:61], v[2:5], v[38:41]
	s_nop 0
	s_nop 6
	v_add_f32_e32 v34, v242, v38
	v_add_f32_e32 v35, v243, v39
	v_mul_f32_e32 v34, 0xbfb8aa3b, v34
	v_mul_f32_e32 v35, 0xbfb8aa3b, v35
	v_exp_f32_e32 v34, v34
	v_exp_f32_e32 v35, v35
	v_lshlrev_b32_e32 v38, 16, v56
	v_and_b32_e32 v39, 0xffff0000, v56
	v_pk_add_f32 v[34:35], v[34:35], 1.0 op_sel_hi:[1,0]
	s_nop 0
	v_rcp_f32_e32 v35, v35
	v_rcp_f32_e32 v34, v34
	s_nop 0
	v_pk_mul_f32 v[34:35], v[34:35], v[38:39]
	v_lshlrev_b32_e32 v38, 16, v57
	v_cvt_pk_bf16_f32 v34, v34, v35
	v_add_f32_e32 v35, v244, v40
	v_mul_f32_e32 v35, 0xbfb8aa3b, v35
	v_exp_f32_e32 v36, v35
	v_add_f32_e32 v35, v245, v41
	v_mul_f32_e32 v35, 0xbfb8aa3b, v35
	v_exp_f32_e32 v37, v35
	v_and_b32_e32 v39, 0xffff0000, v57
	v_pk_add_f32 v[36:37], v[36:37], 1.0 op_sel_hi:[1,0]
	s_nop 0
	v_rcp_f32_e32 v37, v37
	v_rcp_f32_e32 v36, v36
	s_nop 0
	v_pk_mul_f32 v[36:37], v[36:37], v[38:39]
	s_nop 0
	v_cvt_pk_bf16_f32 v35, v36, v37
	global_store_dwordx2 v[50:51], v[34:35], off offset:416
	ds_read_b128 v[38:41], v134
	ds_read_b128 v[56:59], v135
	s_waitcnt lgkmcnt(1)
	v_mfma_f32_16x16x32_bf16 v[38:41], v[38:41], v[30:33], 0
	s_waitcnt lgkmcnt(0)
	v_mfma_f32_16x16x32_bf16 v[38:41], v[56:59], v[26:29], v[38:41]
	ds_read_b128 v[56:59], v136
	s_waitcnt lgkmcnt(0)
	v_mfma_f32_16x16x32_bf16 v[38:41], v[56:59], v[22:25], v[38:41]
	ds_read_b128 v[56:59], v137
	s_waitcnt lgkmcnt(0)
	v_mfma_f32_16x16x32_bf16 v[38:41], v[56:59], v[18:21], v[38:41]
	ds_read_b128 v[56:59], v138
	s_waitcnt lgkmcnt(0)
	v_mfma_f32_16x16x32_bf16 v[38:41], v[56:59], v[14:17], v[38:41]
	ds_read_b128 v[56:59], v139
	s_waitcnt lgkmcnt(0)
	v_mfma_f32_16x16x32_bf16 v[38:41], v[56:59], v[10:13], v[38:41]
	ds_read_b128 v[56:59], v140
	s_waitcnt lgkmcnt(0)
	v_mfma_f32_16x16x32_bf16 v[38:41], v[56:59], v[6:9], v[38:41]
	ds_read_b128 v[56:59], v141
	s_waitcnt lgkmcnt(0)
	v_mfma_f32_16x16x32_bf16 v[38:41], v[56:59], v[2:5], v[38:41]
	s_nop 0
	s_nop 6
	v_add_f32_e32 v34, v246, v38
	v_add_f32_e32 v35, v247, v39
	v_mul_f32_e32 v34, 0xbfb8aa3b, v34
	v_mul_f32_e32 v35, 0xbfb8aa3b, v35
	v_exp_f32_e32 v34, v34
	v_exp_f32_e32 v35, v35
	v_lshlrev_b32_e32 v38, 16, v54
	v_and_b32_e32 v39, 0xffff0000, v54
	v_pk_add_f32 v[34:35], v[34:35], 1.0 op_sel_hi:[1,0]
	s_nop 0
	v_rcp_f32_e32 v35, v35
	v_rcp_f32_e32 v34, v34
	s_nop 0
	v_pk_mul_f32 v[34:35], v[34:35], v[38:39]
	v_lshlrev_b32_e32 v38, 16, v55
	v_cvt_pk_bf16_f32 v34, v34, v35
	v_add_f32_e32 v35, v248, v40
	v_mul_f32_e32 v35, 0xbfb8aa3b, v35
	v_exp_f32_e32 v36, v35
	v_add_f32_e32 v35, v249, v41
	v_mul_f32_e32 v35, 0xbfb8aa3b, v35
	v_exp_f32_e32 v37, v35
	v_and_b32_e32 v39, 0xffff0000, v55
	v_pk_add_f32 v[36:37], v[36:37], 1.0 op_sel_hi:[1,0]
	s_nop 0
	v_rcp_f32_e32 v37, v37
	v_rcp_f32_e32 v36, v36
	s_nop 0
	v_pk_mul_f32 v[36:37], v[36:37], v[38:39]
	s_nop 0
	v_cvt_pk_bf16_f32 v35, v36, v37
	global_store_dwordx2 v[50:51], v[34:35], off offset:448
	ds_read_b128 v[38:41], v142
	s_waitcnt lgkmcnt(0)
	v_mfma_f32_16x16x32_bf16 v[30:33], v[38:41], v[30:33], 0
	ds_read_b128 v[38:41], v143
	s_waitcnt lgkmcnt(0)
	v_mfma_f32_16x16x32_bf16 v[26:29], v[38:41], v[26:29], v[30:33]
	s_nop 4
	ds_read_b128 v[30:33], v144
	s_waitcnt lgkmcnt(0)
	v_mfma_f32_16x16x32_bf16 v[22:25], v[30:33], v[22:25], v[26:29]
	s_nop 2
	ds_read_b128 v[26:29], v145
	s_waitcnt lgkmcnt(0)
	v_mfma_f32_16x16x32_bf16 v[18:21], v[26:29], v[18:21], v[22:25]
	s_nop 2
	ds_read_b128 v[22:25], v146
	s_waitcnt lgkmcnt(0)
	v_mfma_f32_16x16x32_bf16 v[14:17], v[22:25], v[14:17], v[18:21]
	s_nop 2
	ds_read_b128 v[18:21], v147
	s_waitcnt lgkmcnt(0)
	v_mfma_f32_16x16x32_bf16 v[10:13], v[18:21], v[10:13], v[14:17]
	s_nop 2
	ds_read_b128 v[14:17], v148
	s_waitcnt lgkmcnt(0)
	v_mfma_f32_16x16x32_bf16 v[6:9], v[14:17], v[6:9], v[10:13]
	s_nop 2
	ds_read_b128 v[10:13], v149
	s_waitcnt lgkmcnt(0)
	v_mfma_f32_16x16x32_bf16 v[2:5], v[10:13], v[2:5], v[6:9]
	s_nop 2
	v_lshlrev_b32_e32 v6, 16, v52
	v_and_b32_e32 v7, 0xffff0000, v52
	s_nop 0
	s_nop 1
	v_add_f32_e32 v2, v250, v2
	v_add_f32_e32 v3, v251, v3
	v_mul_f32_e32 v2, 0xbfb8aa3b, v2
	v_mul_f32_e32 v3, 0xbfb8aa3b, v3
	v_exp_f32_e32 v2, v2
	v_exp_f32_e32 v3, v3
	s_nop 0
	v_pk_add_f32 v[2:3], v[2:3], 1.0 op_sel_hi:[1,0]
	s_nop 0
	v_rcp_f32_e32 v3, v3
	v_rcp_f32_e32 v2, v2
	s_nop 0
	v_pk_mul_f32 v[2:3], v[2:3], v[6:7]
	v_lshlrev_b32_e32 v6, 16, v53
	v_cvt_pk_bf16_f32 v2, v2, v3
	v_add_f32_e32 v3, v252, v4
	v_mul_f32_e32 v3, 0xbfb8aa3b, v3
	v_exp_f32_e32 v4, v3
	v_add_f32_e32 v3, v253, v5
	v_mul_f32_e32 v3, 0xbfb8aa3b, v3
	v_exp_f32_e32 v5, v3
	v_and_b32_e32 v7, 0xffff0000, v53
	v_pk_add_f32 v[4:5], v[4:5], 1.0 op_sel_hi:[1,0]
	s_nop 0
	v_rcp_f32_e32 v5, v5
	v_rcp_f32_e32 v4, v4
	s_nop 0
	v_pk_mul_f32 v[4:5], v[4:5], v[6:7]
	v_cmp_lt_i32_e32 vcc, s3, v84
	v_cvt_pk_bf16_f32 v3, v4, v5
	global_store_dwordx2 v[50:51], v[2:3], off offset:480
	s_or_b64 s[22:23], vcc, s[22:23]
	s_andn2_b64 exec, exec, s[22:23]
	s_cbranch_execnz .LBB0_298

.LBB0_443:
	v_mov_b32_e32 v33, v1
	v_lshl_add_u64 v[2:3], v[2:3], 1, v[40:41]
	v_lshl_add_u64 v[40:41], s[68:69], 0, v[32:33]
	v_lshl_add_u64 v[32:33], s[70:71], 0, v[0:1]
	s_movk_i32 s10, 0xffbe
	v_lshl_add_u64 v[32:33], v[46:47], 1, v[32:33]
	v_mov_b32_e32 v49, v1
	v_mul_lo_u32 v0, v186, s10
	s_movk_i32 s10, 0x840
	v_mul_u32_u24_e32 v55, 0x84, v42
	v_add_u32_e32 v56, 0x41, v84
	v_lshl_add_u64 v[42:43], v[34:35], 1, v[68:69]
	v_lshl_add_u64 v[44:45], v[44:45], 1, s[84:85]
	v_lshl_add_u64 v[46:47], v[32:33], 0, v[48:49]
	v_mul_lo_u32 v57, v186, s10
	s_mov_b64 s[10:11], 0
	s_waitcnt vmcnt(0)
	s_branch .LBB0_445
.LBB0_444:
	s_or_b64 exec, exec, s[14:15]
	s_setprio 0
	v_add_u32_e32 v0, -1, v0
	s_and_b64 vcc, exec, s[62:63]
	s_cbranch_vccnz .Lgla_wait_all
	s_waitcnt vmcnt(2)
	s_branch .Lgla_wait_done

.Lgla_wait_done:
	v_mov_b64_e32 v[28:29], v[48:49]
	v_mov_b64_e32 v[30:31], v[50:51]
	v_mov_b32_e32 v84, v83
	s_andn2_b64 exec, exec, s[10:11]
	s_cbranch_execz .LBB0_474

.LBB0_452:
	s_or_b64 s[14:15], s[14:15], exec
	ds_write_b128 v137, v[12:15]
.LBB0_453:
	s_and_saveexec_b64 s[18:19], s[14:15]
	s_cbranch_execz .LBB0_455
	ds_write_b128 v138, v[16:19]
.LBB0_455:
	s_or_b64 exec, exec, s[18:19]
	ds_write_b128 v139, v[20:23] offset:9216
	ds_write_b128 v182, v[24:27] offset:18432
	s_and_saveexec_b64 s[14:15], s[48:49]
	ds_write_b32 v131, v53 offset:32768
	s_or_b64 exec, exec, s[14:15]
	v_add_u32_e32 v83, 1, v84
	v_cmp_lt_i32_e32 vcc, v84, v56
	v_cmp_ge_i32_e64 s[64:65], v84, v56
	v_mov_b64_e32 v[48:49], v[28:29]
	v_mov_b64_e32 v[50:51], v[30:31]
	s_and_saveexec_b64 s[14:15], vcc
	s_cbranch_execz .LBB0_470
	v_cmp_gt_i32_e32 vcc, 3, v84
	s_nop 1
	v_cndmask_b32_e64 v20, v217, 3, vcc
	v_add3_u32 v20, v20, v0, -1
	v_cndmask_b32_e64 v20, v20, v83, s[60:61]
	v_add_u32_e32 v34, v20, v55
	v_mul_hi_i32 v20, v34, s7
	v_lshrrev_b32_e32 v21, 31, v20
	v_ashrrev_i32_e32 v20, 5, v20
	v_add_u32_e32 v20, v20, v21
	v_mul_lo_u32 v21, v20, s17
	v_sub_u32_e32 v21, v34, v21
	v_cmp_lt_i32_e32 vcc, 3, v21
	v_lshlrev_b32_e32 v21, 6, v21
	s_and_saveexec_b64 s[18:19], vcc
	s_xor_b64 s[18:19], exec, s[18:19]
	v_lshlrev_b32_e32 v20, 13, v20
	s_movk_i32 s30, 0xff00
	v_add3_u32 v33, v21, v20, s30
	s_andn2_saveexec_b64 s[18:19], s[18:19]
	v_lshlrev_b32_e32 v20, 8, v20
	s_mov_b32 s30, 0x8000
	v_add3_u32 v33, v20, v21, s30
	s_or_b64 exec, exec, s[18:19]
	s_movk_i32 s18, 0x300
	v_mad_i64_i32 v[20:21], s[18:19], v33, s18, 0
	s_and_b64 vcc, exec, s[62:63]
	s_mov_b64 s[18:19], s[26:27]
	s_cbranch_vccnz .LBB0_464
	v_lshl_add_u64 v[12:13], v[40:41], 0, v[20:21]
	global_load_dwordx4 v[12:15], v[12:13], off
	s_or_b64 s[18:19], s[26:27], exec

.LBB0_511:
	v_or_b32_e32 v98, v46, v83
	s_movk_i32 s10, 0xffd4
	v_lshlrev_b32_e32 v46, 4, v98
	v_mov_b32_e32 v47, v1
	v_mul_lo_u32 v194, v186, s10
	s_movk_i32 s10, 0x580
	v_mul_u32_u24_e32 v192, 0x84, v53
	s_mov_b32 s18, 44
	v_add_u32_e32 v193, 44, v52
	v_mov_b32_e32 v99, v1
	v_lshl_add_u64 v[100:101], v[48:49], 1, v[50:51]
	v_lshl_add_u64 v[102:103], s[90:91], 0, v[46:47]
	v_mul_lo_u32 v195, v186, s10
	v_mov_b32_e32 v57, 0
	s_waitcnt vmcnt(0)

.LBB0_518:
	s_and_b64 vcc, exec, s[60:61]
	ds_write_b128 v171, v[30:33] offset:13312
	s_cbranch_vccnz .LBB0_520

.LBB0_550:
	ds_write_b128 v170, v[14:17]
	ds_write_b128 v170, v[26:29] offset:13312
	ds_write_b128 v171, v[18:21]
	s_cbranch_execnz .LBB0_518
.LBB0_551:
	ds_write_b128 v170, v[26:29] offset:13312
	s_and_b64 vcc, exec, s[60:61]
	ds_write_b128 v171, v[30:33] offset:13312
	s_cbranch_vccz .LBB0_519
	s_branch .LBB0_520

.LBB0_554:
	s_and_b64 vcc, exec, s[60:61]
	s_cbranch_vccnz .Lml_wait_all
	s_waitcnt vmcnt(2)
	s_branch .Lml_wait_done

.Lml_wait_done:
	v_mov_b32_e32 v96, v91
	v_mov_b64_e32 v[104:105], v[108:109]
	v_mov_b64_e32 v[106:107], v[110:111]
	v_mov_b32_e32 v52, v196
	s_branch .LBB0_512

	.amdhsa_kernel _Z4mega6Params
		.amdhsa_group_segment_fixed_size 0
		.amdhsa_private_segment_fixed_size 0
		.amdhsa_kernarg_size 632
		.amdhsa_user_sgpr_count 2
		.amdhsa_user_sgpr_dispatch_ptr 0
		.amdhsa_user_sgpr_queue_ptr 0
		.amdhsa_user_sgpr_kernarg_segment_ptr 1
		.amdhsa_user_sgpr_dispatch_id 0
		.amdhsa_user_sgpr_kernarg_preload_length 0
		.amdhsa_user_sgpr_kernarg_preload_offset 0
		.amdhsa_user_sgpr_private_segment_size 0
		.amdhsa_uses_dynamic_stack 0
		.amdhsa_enable_private_segment 0
		.amdhsa_system_sgpr_workgroup_id_x 1
		.amdhsa_system_sgpr_workgroup_id_y 0
		.amdhsa_system_sgpr_workgroup_id_z 0
		.amdhsa_system_sgpr_workgroup_info 0
		.amdhsa_system_vgpr_workitem_id 2
		.amdhsa_next_free_vgpr 256
		.amdhsa_next_free_sgpr 100
		.amdhsa_accum_offset 256
		.amdhsa_reserve_vcc 1
		.amdhsa_float_round_mode_32 0
		.amdhsa_float_round_mode_16_64 0
		.amdhsa_float_denorm_mode_32 3
		.amdhsa_float_denorm_mode_16_64 3
		.amdhsa_dx10_clamp 1
		.amdhsa_ieee_mode 1
		.amdhsa_fp16_overflow 0
		.amdhsa_tg_split 0
		.amdhsa_exception_fp_ieee_invalid_op 0
		.amdhsa_exception_fp_denorm_src 0
		.amdhsa_exception_fp_ieee_div_zero 0
		.amdhsa_exception_fp_ieee_overflow 0
		.amdhsa_exception_fp_ieee_underflow 0
		.amdhsa_exception_fp_ieee_inexact 0
		.amdhsa_exception_int_div_zero 0
	.end_amdhsa_kernel

amdhsa.kernels:
  - .agpr_count:     0
    .args:
      - .offset:         0
        .size:           376
        .value_kind:     by_value
      - .offset:         376
        .size:           4
        .value_kind:     hidden_block_count_x
      - .offset:         380
        .size:           4
        .value_kind:     hidden_block_count_y
      - .offset:         384
        .size:           4
        .value_kind:     hidden_block_count_z
      - .offset:         388
        .size:           2
        .value_kind:     hidden_group_size_x
      - .offset:         390
        .size:           2
        .value_kind:     hidden_group_size_y
      - .offset:         392
        .size:           2
        .value_kind:     hidden_group_size_z
      - .offset:         394
        .size:           2
        .value_kind:     hidden_remainder_x
      - .offset:         396
        .size:           2
        .value_kind:     hidden_remainder_y
      - .offset:         398
        .size:           2
        .value_kind:     hidden_remainder_z
      - .offset:         416
        .size:           8
        .value_kind:     hidden_global_offset_x
      - .offset:         424
        .size:           8
        .value_kind:     hidden_global_offset_y
      - .offset:         432
        .size:           8
        .value_kind:     hidden_global_offset_z
      - .offset:         440
        .size:           2
        .value_kind:     hidden_grid_dims
      - .offset:         464
        .size:           8
        .value_kind:     hidden_multigrid_sync_arg
      - .offset:         496
        .size:           4
        .value_kind:     hidden_dynamic_lds_size
    .group_segment_fixed_size: 0
    .kernarg_segment_align: 8
    .kernarg_segment_size: 632
    .language:       OpenCL C
    .language_version:
      - 2
      - 0
    .max_flat_workgroup_size: 512
    .name:           _Z4mega6Params
    .private_segment_fixed_size: 0
    .sgpr_count:     106
    .sgpr_spill_count: 91
    .symbol:         _Z4mega6Params.kd
    .uniform_work_group_size: 1
    .uses_dynamic_stack: false
    .vgpr_count:     256
    .vgpr_spill_count: 0
    .wavefront_size: 64
